# LoRA a/g epilogue: the gate output g (read once, two phases later) is stored nt so it does not displace the scan's inputs from the caches
# baseline (speedup 1.0000x reference)
; #define PG8_STAGE(bufoff, gbase, voff) do { _Pragma("unroll") for (int _i = 0; _i < 2; ++_i) \
;         __builtin_amdgcn_global_load_lds((const unsigned*)((const char*)(gbase) + (voff)[_i]), (PG8_LAS unsigned*)(lds + (bufoff) + ldsw + _i * 8192), 16, 0, 0); } while (0)
; #define PG8_LDA(dst, b, h) do { _Pragma("unroll") for (int m = 0; m < 4; ++m) _Pragma("unroll") for (int k = 0; k < 2; ++k) dst[m][k] = *(const PG8_LAS bf16x8*)(lds + PG8_SA(b, h) + aoff + m * 2048 + k * 1024); } while (0)
; #define PG8_LDB(dst, b, h) do { _Pragma("unroll") for (int n = 0; n < 2; ++n) _Pragma("unroll") for (int k = 0; k < 2; ++k) dst[n][k] = *(const PG8_LAS bf16x8*)(lds + PG8_SB(b, h) + boff + n * 2048 + k * 1024); } while (0)
; #define PG8_WAIT_V(n) asm volatile("s_waitcnt vmcnt(" #n ")" ::: "memory")
; #define PG8_WAIT_L(n) asm volatile("s_waitcnt lgkmcnt(" #n ")" ::: "memory")
; #define PG8_BAR __builtin_amdgcn_s_barrier()
; #define PG8_SCHED __builtin_amdgcn_sched_barrier(0)
; template <class Epi, class Sched>
; __device__ __forceinline__ void gemm_phase(PG8_LAS unsigned char* lds, const Gemm g, const Sched& S, const Epi& E) {
;     ...
;             PG8_LDB(B0, 0, 0); PG8_SCHED; PG8_LDA(At, 0, 0); PG8_STAGE(PG8_SA(1, 1), a1 + hstep, voffA);
;             PG8_WAIT_L(8); PG8_BAR; PG8_WAIT_L(0); PG8_MMA(0, 0, At, B0); PG8_BAR; PG8_SCHED;
;             PG8_LDB(B1, 0, 1); PG8_STAGE(PG8_SB(0, 0), b2, voffB);
;             PG8_BAR; PG8_WAIT_L(0); PG8_MMA(0, 1, At, B1); PG8_BAR;
;             PG8_LDA(At, 0, 1); PG8_STAGE(PG8_SA(0, 0), a2, voffA);
;             PG8_BAR; PG8_WAIT_L(0); PG8_MMA(1, 0, At, B0); PG8_BAR; PG8_SCHED;
;             PG8_STAGE(PG8_SB(0, 1), b2 + hstep, voffB);
;             PG8_WAIT_V(6); PG8_BAR; PG8_MMA(1, 1, At, B1); PG8_BAR;
;             PG8_LDB(B0, 1, 0); PG8_SCHED; PG8_LDA(At, 1, 0); PG8_STAGE(PG8_SA(0, 1), a2 + hstep, voffA);
;             PG8_WAIT_L(8); PG8_BAR; PG8_WAIT_L(0); PG8_MMA(0, 0, At, B0); PG8_BAR; PG8_SCHED;
;             PG8_LDB(B1, 1, 1); PG8_STAGE(PG8_SB(1, 0), b3, voffB);
;             PG8_BAR; PG8_WAIT_L(0); PG8_MMA(0, 1, At, B1); PG8_BAR;
;             PG8_LDA(At, 1, 1); PG8_STAGE(PG8_SA(1, 0), a3, voffA);
;             PG8_BAR; PG8_WAIT_L(0); PG8_MMA(1, 0, At, B0); PG8_BAR; PG8_SCHED;
;             PG8_STAGE(PG8_SB(1, 1), b3 + hstep, voffB);
;             PG8_WAIT_V(6); PG8_BAR; PG8_MMA(1, 1, At, B1); PG8_BAR;
.LBB0_461:
	ds_read_b128 v[8:11], v106
	ds_read_b128 v[12:15], v106 offset:1024
	ds_read_b128 v[16:19], v106 offset:2048
	ds_read_b128 v[20:23], v106 offset:3072
	s_add_u32 s72, s24, 0x18080
	s_addc_u32 s73, s25, 0
	s_add_i32 s79, s38, 0xc000
	v_lshl_add_u64 v[0:1], s[72:73], 0, v[64:65]
	s_mov_b32 m0, s79
	ds_read_b128 v[4:7], v105
	ds_read_b128 v[24:27], v105 offset:1024
	ds_read_b128 v[28:31], v105 offset:2048
	ds_read_b128 v[32:35], v105 offset:3072
	ds_read_b128 v[36:39], v105 offset:4096
	ds_read_b128 v[40:43], v105 offset:5120
	ds_read_b128 v[44:47], v105 offset:6144
	ds_read_b128 v[48:51], v105 offset:7168
	global_load_lds_dwordx4 v[0:1], off
	v_lshl_add_u64 v[0:1], s[72:73], 0, v[68:69]
	s_add_i32 s72, s38, 0xe000
	s_mov_b32 m0, s72
	s_nop 0
	global_load_lds_dwordx4 v[0:1], off
	s_waitcnt lgkmcnt(8)
	s_barrier
	s_waitcnt lgkmcnt(0)
	v_mfma_f32_16x16x32_bf16 v[0:3], v[8:11], v[4:7], 0
	v_mfma_f32_16x16x32_bf16 v[52:55], v[12:15], v[24:27], v[0:3]
	v_mfma_f32_16x16x32_bf16 v[0:3], v[16:19], v[4:7], 0
	v_mfma_f32_16x16x32_bf16 v[56:59], v[20:23], v[24:27], v[0:3]
	v_mfma_f32_16x16x32_bf16 v[0:3], v[8:11], v[28:31], 0
	v_mfma_f32_16x16x32_bf16 v[60:63], v[12:15], v[32:35], v[0:3]
	v_mfma_f32_16x16x32_bf16 v[0:3], v[16:19], v[28:31], 0
	v_mfma_f32_16x16x32_bf16 v[78:81], v[20:23], v[32:35], v[0:3]
	v_mfma_f32_16x16x32_bf16 v[0:3], v[8:11], v[36:39], 0
	v_mfma_f32_16x16x32_bf16 v[82:85], v[12:15], v[40:43], v[0:3]
	v_mfma_f32_16x16x32_bf16 v[0:3], v[16:19], v[36:39], 0
	v_mfma_f32_16x16x32_bf16 v[86:89], v[20:23], v[40:43], v[0:3]
	v_mfma_f32_16x16x32_bf16 v[0:3], v[8:11], v[44:47], 0
	v_mfma_f32_16x16x32_bf16 v[90:93], v[12:15], v[48:51], v[0:3]
	v_mfma_f32_16x16x32_bf16 v[0:3], v[16:19], v[44:47], 0
	v_mfma_f32_16x16x32_bf16 v[94:97], v[20:23], v[48:51], v[0:3]
	s_barrier
	s_nop 4
	v_lshl_add_u64 v[0:1], s[26:27], 0, v[66:67]
	s_add_i32 s75, s66, s37
	v_lshl_add_u64 v[2:3], v[0:1], 0, s[14:15]
	s_mov_b32 m0, s75
	ds_read_b128 v[98:101], v107
	ds_read_b128 v[108:111], v107 offset:1024
	ds_read_b128 v[112:115], v107 offset:2048
	ds_read_b128 v[116:119], v107 offset:3072
	global_load_lds_dwordx4 v[2:3], off
	v_lshl_add_u64 v[2:3], s[26:27], 0, v[70:71]
	s_add_i32 s73, s75, 0x2000
	v_lshl_add_u64 v[120:121], v[2:3], 0, s[14:15]
	s_mov_b32 m0, s73
	s_nop 0
	global_load_lds_dwordx4 v[120:121], off
	s_barrier
	s_waitcnt lgkmcnt(0)
	v_mfma_f32_16x16x32_bf16 v[120:123], v[98:101], v[4:7], 0
	v_mfma_f32_16x16x32_bf16 v[4:7], v[112:115], v[4:7], 0
	v_mfma_f32_16x16x32_bf16 v[120:123], v[108:111], v[24:27], v[120:123]
	v_mfma_f32_16x16x32_bf16 v[24:27], v[116:119], v[24:27], v[4:7]
	v_mfma_f32_16x16x32_bf16 v[4:7], v[98:101], v[28:31], 0
	v_mfma_f32_16x16x32_bf16 v[124:127], v[108:111], v[32:35], v[4:7]
	v_mfma_f32_16x16x32_bf16 v[4:7], v[112:115], v[28:31], 0
	v_mfma_f32_16x16x32_bf16 v[28:31], v[116:119], v[32:35], v[4:7]
	v_mfma_f32_16x16x32_bf16 v[4:7], v[98:101], v[36:39], 0
	v_mfma_f32_16x16x32_bf16 v[32:35], v[108:111], v[40:43], v[4:7]
	v_mfma_f32_16x16x32_bf16 v[4:7], v[112:115], v[36:39], 0
	v_mfma_f32_16x16x32_bf16 v[36:39], v[116:119], v[40:43], v[4:7]
	v_mfma_f32_16x16x32_bf16 v[4:7], v[98:101], v[44:47], 0
	v_mfma_f32_16x16x32_bf16 v[40:43], v[108:111], v[48:51], v[4:7]
	v_mfma_f32_16x16x32_bf16 v[4:7], v[112:115], v[44:47], 0
	v_mfma_f32_16x16x32_bf16 v[44:47], v[116:119], v[48:51], v[4:7]
	s_nop 5
	v_lshl_add_u64 v[4:5], s[24:25], 0, v[64:65]
	s_mov_b32 m0, s38
	v_lshl_add_u64 v[6:7], v[4:5], 0, s[14:15]
	s_barrier
	ds_read_b128 v[48:51], v105 offset:16384
	ds_read_b128 v[128:131], v105 offset:17408
	ds_read_b128 v[132:135], v105 offset:18432
	ds_read_b128 v[136:139], v105 offset:19456
	ds_read_b128 v[140:143], v105 offset:20480
	ds_read_b128 v[144:147], v105 offset:21504
	ds_read_b128 v[148:151], v105 offset:22528
	ds_read_b128 v[152:155], v105 offset:23552
	global_load_lds_dwordx4 v[6:7], off
	v_lshl_add_u64 v[6:7], s[24:25], 0, v[68:69]
	v_lshl_add_u64 v[156:157], v[6:7], 0, s[14:15]
	s_mov_b32 m0, s39
	s_nop 0
	global_load_lds_dwordx4 v[156:157], off
	s_barrier
	s_waitcnt lgkmcnt(0)
	v_mfma_f32_16x16x32_bf16 v[156:159], v[8:11], v[48:51], 0
	v_mfma_f32_16x16x32_bf16 v[164:167], v[8:11], v[132:135], 0
	v_mfma_f32_16x16x32_bf16 v[172:175], v[8:11], v[140:143], 0
	v_mfma_f32_16x16x32_bf16 v[8:11], v[8:11], v[148:151], 0
	v_mfma_f32_16x16x32_bf16 v[156:159], v[12:15], v[128:131], v[156:159]
	v_mfma_f32_16x16x32_bf16 v[160:163], v[16:19], v[48:51], 0
	v_mfma_f32_16x16x32_bf16 v[164:167], v[12:15], v[136:139], v[164:167]
	v_mfma_f32_16x16x32_bf16 v[168:171], v[16:19], v[132:135], 0
	v_mfma_f32_16x16x32_bf16 v[172:175], v[12:15], v[144:147], v[172:175]
	v_mfma_f32_16x16x32_bf16 v[176:179], v[16:19], v[140:143], 0
	v_mfma_f32_16x16x32_bf16 v[10:13], v[12:15], v[152:155], v[8:11]
	v_mfma_f32_16x16x32_bf16 v[14:17], v[16:19], v[148:151], 0
	v_mfma_f32_16x16x32_bf16 v[160:163], v[20:23], v[128:131], v[160:163]
	v_mfma_f32_16x16x32_bf16 v[168:171], v[20:23], v[136:139], v[168:171]
	v_mfma_f32_16x16x32_bf16 v[176:179], v[20:23], v[144:147], v[176:179]
	v_mfma_f32_16x16x32_bf16 v[14:17], v[20:23], v[152:155], v[14:17]
	s_barrier
	s_add_u32 s80, s26, 0x18100
	s_addc_u32 s81, s27, 0
	s_add_i32 s76, s67, s37
	v_lshl_add_u64 v[8:9], s[80:81], 0, v[66:67]
	s_mov_b32 m0, s76
	s_add_i32 s74, s76, 0x2000
	global_load_lds_dwordx4 v[8:9], off
	v_lshl_add_u64 v[8:9], s[80:81], 0, v[70:71]
	s_mov_b32 m0, s74
	s_nop 0
	global_load_lds_dwordx4 v[8:9], off
	s_waitcnt vmcnt(6)
	s_barrier
; #define PG8_STAGE(bufoff, gbase, voff) do { _Pragma("unroll") for (int _i = 0; _i < 2; ++_i) \
;         __builtin_amdgcn_global_load_lds((const unsigned*)((const char*)(gbase) + (voff)[_i]), (PG8_LAS unsigned*)(lds + (bufoff) + ldsw + _i * 8192), 16, 0, 0); } while (0)
; #define PG8_LDA(dst, b, h) do { _Pragma("unroll") for (int m = 0; m < 4; ++m) _Pragma("unroll") for (int k = 0; k < 2; ++k) dst[m][k] = *(const PG8_LAS bf16x8*)(lds + PG8_SA(b, h) + aoff + m * 2048 + k * 1024); } while (0)
; #define PG8_LDB(dst, b, h) do { _Pragma("unroll") for (int n = 0; n < 2; ++n) _Pragma("unroll") for (int k = 0; k < 2; ++k) dst[n][k] = *(const PG8_LAS bf16x8*)(lds + PG8_SB(b, h) + boff + n * 2048 + k * 1024); } while (0)
; #define PG8_WAIT_V(n) asm volatile("s_waitcnt vmcnt(" #n ")" ::: "memory")
; #define PG8_WAIT_L(n) asm volatile("s_waitcnt lgkmcnt(" #n ")" ::: "memory")
; #define PG8_BAR __builtin_amdgcn_s_barrier()
; #define PG8_SCHED __builtin_amdgcn_sched_barrier(0)
; template <class Epi, class Sched>
; __device__ __forceinline__ void gemm_phase(PG8_LAS unsigned char* lds, const Gemm g, const Sched& S, const Epi& E) {
;     ...
;             PG8_LDB(B0, 0, 0); PG8_SCHED; PG8_LDA(At, 0, 0); PG8_STAGE(PG8_SA(1, 1), a1 + hstep, voffA);
;             PG8_WAIT_L(8); PG8_BAR; PG8_WAIT_L(0); PG8_MMA(0, 0, At, B0); PG8_BAR; PG8_SCHED;
;             PG8_LDB(B1, 0, 1); PG8_STAGE(PG8_SB(0, 0), b2, voffB);
;             PG8_BAR; PG8_WAIT_L(0); PG8_MMA(0, 1, At, B1); PG8_BAR;
;             PG8_LDA(At, 0, 1); PG8_STAGE(PG8_SA(0, 0), a2, voffA);
;             PG8_BAR; PG8_WAIT_L(0); PG8_MMA(1, 0, At, B0); PG8_BAR; PG8_SCHED;
;             PG8_STAGE(PG8_SB(0, 1), b2 + hstep, voffB);
;             PG8_WAIT_V(6); PG8_BAR; PG8_MMA(1, 1, At, B1); PG8_BAR;
;             PG8_LDB(B0, 1, 0); PG8_SCHED; PG8_LDA(At, 1, 0); PG8_STAGE(PG8_SA(0, 1), a2 + hstep, voffA);
;             PG8_WAIT_L(8); PG8_BAR; PG8_WAIT_L(0); PG8_MMA(0, 0, At, B0); PG8_BAR; PG8_SCHED;
;             PG8_LDB(B1, 1, 1); PG8_STAGE(PG8_SB(1, 0), b3, voffB);
;             PG8_BAR; PG8_WAIT_L(0); PG8_MMA(0, 1, At, B1); PG8_BAR;
;             PG8_LDA(At, 1, 1); PG8_STAGE(PG8_SA(1, 0), a3, voffA);
;             PG8_BAR; PG8_WAIT_L(0); PG8_MMA(1, 0, At, B0); PG8_BAR; PG8_SCHED;
;             PG8_STAGE(PG8_SB(1, 1), b3 + hstep, voffB);
;             PG8_WAIT_V(6); PG8_BAR; PG8_MMA(1, 1, At, B1); PG8_BAR;
	v_mfma_f32_16x16x32_bf16 v[18:21], v[98:101], v[48:51], 0
	v_mfma_f32_16x16x32_bf16 v[48:51], v[112:115], v[48:51], 0
	v_mfma_f32_16x16x32_bf16 v[18:21], v[108:111], v[128:131], v[18:21]
	v_mfma_f32_16x16x32_bf16 v[48:51], v[116:119], v[128:131], v[48:51]
	v_mfma_f32_16x16x32_bf16 v[128:131], v[98:101], v[132:135], 0
	v_mfma_f32_16x16x32_bf16 v[132:135], v[112:115], v[132:135], 0
	v_mfma_f32_16x16x32_bf16 v[128:131], v[108:111], v[136:139], v[128:131]
	v_mfma_f32_16x16x32_bf16 v[132:135], v[116:119], v[136:139], v[132:135]
	v_mfma_f32_16x16x32_bf16 v[136:139], v[98:101], v[140:143], 0
	v_mfma_f32_16x16x32_bf16 v[98:101], v[98:101], v[148:151], 0
	v_mfma_f32_16x16x32_bf16 v[136:139], v[108:111], v[144:147], v[136:139]
	v_mfma_f32_16x16x32_bf16 v[140:143], v[112:115], v[140:143], 0
	v_mfma_f32_16x16x32_bf16 v[98:101], v[108:111], v[152:155], v[98:101]
	v_mfma_f32_16x16x32_bf16 v[108:111], v[112:115], v[148:151], 0
	v_mfma_f32_16x16x32_bf16 v[140:143], v[116:119], v[144:147], v[140:143]
	v_mfma_f32_16x16x32_bf16 v[108:111], v[116:119], v[152:155], v[108:111]
	s_add_i32 s77, 0, 0x18000
	v_add_u32_e32 v8, s77, v104
	s_barrier
	ds_read_b128 v[112:115], v8
	ds_read_b128 v[116:119], v8 offset:1024
	ds_read_b128 v[144:147], v8 offset:2048
	ds_read_b128 v[148:151], v8 offset:3072
	s_add_u32 s80, s24, 0x18100
	s_addc_u32 s81, s25, 0
	s_mov_b32 m0, s40
	v_lshl_add_u64 v[22:23], s[80:81], 0, v[64:65]
	ds_read_b128 v[152:155], v105 offset:32768
	ds_read_b128 v[180:183], v105 offset:33792
	ds_read_b128 v[184:187], v105 offset:34816
	ds_read_b128 v[188:191], v105 offset:35840
	ds_read_b128 v[192:195], v105 offset:36864
	ds_read_b128 v[196:199], v105 offset:37888
	ds_read_b128 v[200:203], v105 offset:38912
	ds_read_b128 v[204:207], v105 offset:39936
	global_load_lds_dwordx4 v[22:23], off
	v_lshl_add_u64 v[22:23], s[80:81], 0, v[68:69]
	s_mov_b32 m0, s41
	s_nop 0
	global_load_lds_dwordx4 v[22:23], off
	s_waitcnt lgkmcnt(8)
	s_barrier
	s_waitcnt lgkmcnt(0)
	v_mfma_f32_16x16x32_bf16 v[52:55], v[112:115], v[152:155], v[52:55]
	v_mfma_f32_16x16x32_bf16 v[56:59], v[144:147], v[152:155], v[56:59]
	v_mfma_f32_16x16x32_bf16 v[60:63], v[112:115], v[184:187], v[60:63]
	v_mfma_f32_16x16x32_bf16 v[78:81], v[144:147], v[184:187], v[78:81]
	v_mfma_f32_16x16x32_bf16 v[82:85], v[112:115], v[192:195], v[82:85]
	v_mfma_f32_16x16x32_bf16 v[86:89], v[144:147], v[192:195], v[86:89]
	v_mfma_f32_16x16x32_bf16 v[90:93], v[112:115], v[200:203], v[90:93]
	v_mfma_f32_16x16x32_bf16 v[94:97], v[144:147], v[200:203], v[94:97]
	v_mfma_f32_16x16x32_bf16 v[52:55], v[116:119], v[180:183], v[52:55]
	v_mfma_f32_16x16x32_bf16 v[56:59], v[148:151], v[180:183], v[56:59]
	v_mfma_f32_16x16x32_bf16 v[60:63], v[116:119], v[188:191], v[60:63]
	v_mfma_f32_16x16x32_bf16 v[78:81], v[148:151], v[188:191], v[78:81]
	v_mfma_f32_16x16x32_bf16 v[82:85], v[116:119], v[196:199], v[82:85]
	v_mfma_f32_16x16x32_bf16 v[86:89], v[148:151], v[196:199], v[86:89]
	v_mfma_f32_16x16x32_bf16 v[90:93], v[116:119], v[204:207], v[90:93]
	v_mfma_f32_16x16x32_bf16 v[94:97], v[148:151], v[204:207], v[94:97]
	s_barrier
	s_add_i32 s81, 0, 0x1c000
	s_add_i32 s80, s77, s37
	v_add_u32_e32 v9, s81, v104
	v_lshl_add_u64 v[22:23], v[0:1], 0, s[16:17]
	s_mov_b32 m0, s80
	s_add_i32 s77, s80, 0x2000
	ds_read_b128 v[208:211], v9
	ds_read_b128 v[212:215], v9 offset:1024
	ds_read_b128 v[216:219], v9 offset:2048
	ds_read_b128 v[220:223], v9 offset:3072
	global_load_lds_dwordx4 v[22:23], off
	v_lshl_add_u64 v[22:23], v[2:3], 0, s[16:17]
	s_mov_b32 m0, s77
	s_nop 0
	global_load_lds_dwordx4 v[22:23], off
	s_barrier
	s_waitcnt lgkmcnt(0)
	v_mfma_f32_16x16x32_bf16 v[120:123], v[208:211], v[152:155], v[120:123]
	v_mfma_f32_16x16x32_bf16 v[22:25], v[216:219], v[152:155], v[24:27]
	v_mfma_f32_16x16x32_bf16 v[124:127], v[208:211], v[184:187], v[124:127]
	v_mfma_f32_16x16x32_bf16 v[26:29], v[216:219], v[184:187], v[28:31]
	v_mfma_f32_16x16x32_bf16 v[30:33], v[208:211], v[192:195], v[32:35]
	v_mfma_f32_16x16x32_bf16 v[34:37], v[216:219], v[192:195], v[36:39]
	v_mfma_f32_16x16x32_bf16 v[38:41], v[208:211], v[200:203], v[40:43]
	v_mfma_f32_16x16x32_bf16 v[42:45], v[216:219], v[200:203], v[44:47]
	v_mfma_f32_16x16x32_bf16 v[120:123], v[212:215], v[180:183], v[120:123]
	v_mfma_f32_16x16x32_bf16 v[22:25], v[220:223], v[180:183], v[22:25]
	v_mfma_f32_16x16x32_bf16 v[124:127], v[212:215], v[188:191], v[124:127]
	v_mfma_f32_16x16x32_bf16 v[26:29], v[220:223], v[188:191], v[26:29]
	v_mfma_f32_16x16x32_bf16 v[30:33], v[212:215], v[196:199], v[30:33]
	v_mfma_f32_16x16x32_bf16 v[34:37], v[220:223], v[196:199], v[34:37]
	v_mfma_f32_16x16x32_bf16 v[38:41], v[212:215], v[204:207], v[38:41]
	v_mfma_f32_16x16x32_bf16 v[42:45], v[220:223], v[204:207], v[42:45]
	s_mov_b32 m0, s43
	v_lshl_add_u64 v[46:47], v[4:5], 0, s[16:17]
	s_barrier
	ds_read_b128 v[152:155], v105 offset:49152
	ds_read_b128 v[180:183], v105 offset:50176
	ds_read_b128 v[184:187], v105 offset:51200
	ds_read_b128 v[188:191], v105 offset:52224
	ds_read_b128 v[192:195], v105 offset:53248
	ds_read_b128 v[196:199], v105 offset:54272
	ds_read_b128 v[200:203], v105 offset:55296
	ds_read_b128 v[204:207], v105 offset:56320
	global_load_lds_dwordx4 v[46:47], off
	v_lshl_add_u64 v[46:47], v[6:7], 0, s[16:17]
	s_mov_b32 m0, s60
	s_nop 0
	global_load_lds_dwordx4 v[46:47], off
	s_barrier
; #define PG8_STAGE(bufoff, gbase, voff) do { _Pragma("unroll") for (int _i = 0; _i < 2; ++_i) \
;         __builtin_amdgcn_global_load_lds((const unsigned*)((const char*)(gbase) + (voff)[_i]), (PG8_LAS unsigned*)(lds + (bufoff) + ldsw + _i * 8192), 16, 0, 0); } while (0)
; #define PG8_LDA(dst, b, h) do { _Pragma("unroll") for (int m = 0; m < 4; ++m) _Pragma("unroll") for (int k = 0; k < 2; ++k) dst[m][k] = *(const PG8_LAS bf16x8*)(lds + PG8_SA(b, h) + aoff + m * 2048 + k * 1024); } while (0)
; #define PG8_LDB(dst, b, h) do { _Pragma("unroll") for (int n = 0; n < 2; ++n) _Pragma("unroll") for (int k = 0; k < 2; ++k) dst[n][k] = *(const PG8_LAS bf16x8*)(lds + PG8_SB(b, h) + boff + n * 2048 + k * 1024); } while (0)
; #define PG8_WAIT_V(n) asm volatile("s_waitcnt vmcnt(" #n ")" ::: "memory")
; #define PG8_WAIT_L(n) asm volatile("s_waitcnt lgkmcnt(" #n ")" ::: "memory")
; #define PG8_BAR __builtin_amdgcn_s_barrier()
; #define PG8_SCHED __builtin_amdgcn_sched_barrier(0)
; template <class Epi, class Sched>
; __device__ __forceinline__ void gemm_phase(PG8_LAS unsigned char* lds, const Gemm g, const Sched& S, const Epi& E) {
;     ...
;             PG8_LDB(B0, 0, 0); PG8_SCHED; PG8_LDA(At, 0, 0); PG8_STAGE(PG8_SA(1, 1), a1 + hstep, voffA);
;             PG8_WAIT_L(8); PG8_BAR; PG8_WAIT_L(0); PG8_MMA(0, 0, At, B0); PG8_BAR; PG8_SCHED;
;             PG8_LDB(B1, 0, 1); PG8_STAGE(PG8_SB(0, 0), b2, voffB);
;             PG8_BAR; PG8_WAIT_L(0); PG8_MMA(0, 1, At, B1); PG8_BAR;
;             PG8_LDA(At, 0, 1); PG8_STAGE(PG8_SA(0, 0), a2, voffA);
;             PG8_BAR; PG8_WAIT_L(0); PG8_MMA(1, 0, At, B0); PG8_BAR; PG8_SCHED;
;             PG8_STAGE(PG8_SB(0, 1), b2 + hstep, voffB);
;             PG8_WAIT_V(6); PG8_BAR; PG8_MMA(1, 1, At, B1); PG8_BAR;
;             PG8_LDB(B0, 1, 0); PG8_SCHED; PG8_LDA(At, 1, 0); PG8_STAGE(PG8_SA(0, 1), a2 + hstep, voffA);
;             PG8_WAIT_L(8); PG8_BAR; PG8_WAIT_L(0); PG8_MMA(0, 0, At, B0); PG8_BAR; PG8_SCHED;
;             PG8_LDB(B1, 1, 1); PG8_STAGE(PG8_SB(1, 0), b3, voffB);
;             PG8_BAR; PG8_WAIT_L(0); PG8_MMA(0, 1, At, B1); PG8_BAR;
;             PG8_LDA(At, 1, 1); PG8_STAGE(PG8_SA(1, 0), a3, voffA);
;             PG8_BAR; PG8_WAIT_L(0); PG8_MMA(1, 0, At, B0); PG8_BAR; PG8_SCHED;
;             PG8_STAGE(PG8_SB(1, 1), b3 + hstep, voffB);
;             PG8_WAIT_V(6); PG8_BAR; PG8_MMA(1, 1, At, B1); PG8_BAR;
	s_waitcnt lgkmcnt(0)
	v_mfma_f32_16x16x32_bf16 v[156:159], v[112:115], v[152:155], v[156:159]
	v_mfma_f32_16x16x32_bf16 v[160:163], v[144:147], v[152:155], v[160:163]
	v_mfma_f32_16x16x32_bf16 v[164:167], v[112:115], v[184:187], v[164:167]
	v_mfma_f32_16x16x32_bf16 v[168:171], v[144:147], v[184:187], v[168:171]
	v_mfma_f32_16x16x32_bf16 v[172:175], v[112:115], v[192:195], v[172:175]
	v_mfma_f32_16x16x32_bf16 v[176:179], v[144:147], v[192:195], v[176:179]
	v_mfma_f32_16x16x32_bf16 v[10:13], v[112:115], v[200:203], v[10:13]
	v_mfma_f32_16x16x32_bf16 v[14:17], v[144:147], v[200:203], v[14:17]
	v_mfma_f32_16x16x32_bf16 v[156:159], v[116:119], v[180:183], v[156:159]
	v_mfma_f32_16x16x32_bf16 v[160:163], v[148:151], v[180:183], v[160:163]
	v_mfma_f32_16x16x32_bf16 v[164:167], v[116:119], v[188:191], v[164:167]
	v_mfma_f32_16x16x32_bf16 v[168:171], v[148:151], v[188:191], v[168:171]
	v_mfma_f32_16x16x32_bf16 v[172:175], v[116:119], v[196:199], v[172:175]
	v_mfma_f32_16x16x32_bf16 v[176:179], v[148:151], v[196:199], v[176:179]
	v_mfma_f32_16x16x32_bf16 v[10:13], v[116:119], v[204:207], v[10:13]
	v_mfma_f32_16x16x32_bf16 v[14:17], v[148:151], v[204:207], v[14:17]
	s_barrier
	s_add_u32 s82, s26, 0x18180
	s_addc_u32 s83, s27, 0
	s_add_i32 s81, s81, s37
	v_lshl_add_u64 v[46:47], s[82:83], 0, v[66:67]
	s_mov_b32 m0, s81
	s_add_i32 s78, s81, 0x2000
	global_load_lds_dwordx4 v[46:47], off
	v_lshl_add_u64 v[46:47], s[82:83], 0, v[70:71]
	s_mov_b32 m0, s78
	s_nop 0
	global_load_lds_dwordx4 v[46:47], off
	s_waitcnt vmcnt(6)
	s_barrier
	v_mfma_f32_16x16x32_bf16 v[18:21], v[208:211], v[152:155], v[18:21]
	v_mfma_f32_16x16x32_bf16 v[46:49], v[216:219], v[152:155], v[48:51]
	v_mfma_f32_16x16x32_bf16 v[112:115], v[208:211], v[184:187], v[128:131]
	v_mfma_f32_16x16x32_bf16 v[116:119], v[216:219], v[184:187], v[132:135]
	v_mfma_f32_16x16x32_bf16 v[128:131], v[208:211], v[192:195], v[136:139]
	v_mfma_f32_16x16x32_bf16 v[132:135], v[216:219], v[192:195], v[140:143]
	v_mfma_f32_16x16x32_bf16 v[98:101], v[208:211], v[200:203], v[98:101]
	v_mfma_f32_16x16x32_bf16 v[108:111], v[216:219], v[200:203], v[108:111]
	v_mfma_f32_16x16x32_bf16 v[18:21], v[212:215], v[180:183], v[18:21]
	v_mfma_f32_16x16x32_bf16 v[46:49], v[220:223], v[180:183], v[46:49]
	v_mfma_f32_16x16x32_bf16 v[112:115], v[212:215], v[188:191], v[112:115]
	v_mfma_f32_16x16x32_bf16 v[116:119], v[220:223], v[188:191], v[116:119]
	v_mfma_f32_16x16x32_bf16 v[128:131], v[212:215], v[196:199], v[128:131]
	v_mfma_f32_16x16x32_bf16 v[132:135], v[220:223], v[196:199], v[132:135]
	v_mfma_f32_16x16x32_bf16 v[98:101], v[212:215], v[204:207], v[98:101]
	v_mfma_f32_16x16x32_bf16 v[108:111], v[220:223], v[204:207], v[108:111]
	s_barrier
	ds_read_b128 v[136:139], v106
	ds_read_b128 v[140:143], v106 offset:1024
	ds_read_b128 v[144:147], v106 offset:2048
	ds_read_b128 v[148:151], v106 offset:3072
	s_add_u32 s82, s24, 0x18180
	s_addc_u32 s83, s25, 0
	s_mov_b32 m0, s79
	v_lshl_add_u64 v[50:51], s[82:83], 0, v[64:65]
	ds_read_b128 v[152:155], v105
	ds_read_b128 v[180:183], v105 offset:1024
	ds_read_b128 v[184:187], v105 offset:2048
	ds_read_b128 v[188:191], v105 offset:3072
	ds_read_b128 v[192:195], v105 offset:4096
	ds_read_b128 v[196:199], v105 offset:5120
	ds_read_b128 v[200:203], v105 offset:6144
	ds_read_b128 v[204:207], v105 offset:7168
	global_load_lds_dwordx4 v[50:51], off
	v_lshl_add_u64 v[50:51], s[82:83], 0, v[68:69]
	s_mov_b32 m0, s72
	s_nop 0
	global_load_lds_dwordx4 v[50:51], off
	s_waitcnt lgkmcnt(8)
	s_barrier
	s_waitcnt lgkmcnt(0)
	v_mfma_f32_16x16x32_bf16 v[50:53], v[136:139], v[152:155], v[52:55]
	v_mfma_f32_16x16x32_bf16 v[54:57], v[144:147], v[152:155], v[56:59]
	v_mfma_f32_16x16x32_bf16 v[58:61], v[136:139], v[184:187], v[60:63]
	v_mfma_f32_16x16x32_bf16 v[78:81], v[144:147], v[184:187], v[78:81]
	v_mfma_f32_16x16x32_bf16 v[82:85], v[136:139], v[192:195], v[82:85]
	v_mfma_f32_16x16x32_bf16 v[86:89], v[144:147], v[192:195], v[86:89]
	v_mfma_f32_16x16x32_bf16 v[90:93], v[136:139], v[200:203], v[90:93]
	v_mfma_f32_16x16x32_bf16 v[94:97], v[144:147], v[200:203], v[94:97]
	v_mfma_f32_16x16x32_bf16 v[50:53], v[140:143], v[180:183], v[50:53]
	v_mfma_f32_16x16x32_bf16 v[54:57], v[148:151], v[180:183], v[54:57]
	v_mfma_f32_16x16x32_bf16 v[58:61], v[140:143], v[188:191], v[58:61]
	v_mfma_f32_16x16x32_bf16 v[78:81], v[148:151], v[188:191], v[78:81]
	v_mfma_f32_16x16x32_bf16 v[82:85], v[140:143], v[196:199], v[82:85]
	v_mfma_f32_16x16x32_bf16 v[86:89], v[148:151], v[196:199], v[86:89]
	v_mfma_f32_16x16x32_bf16 v[90:93], v[140:143], v[204:207], v[90:93]
	v_mfma_f32_16x16x32_bf16 v[94:97], v[148:151], v[204:207], v[94:97]
	s_barrier
	s_mov_b32 m0, s75
	v_lshl_add_u64 v[62:63], v[0:1], 0, s[12:13]
	ds_read_b128 v[208:211], v107
	ds_read_b128 v[212:215], v107 offset:1024
	ds_read_b128 v[216:219], v107 offset:2048
	ds_read_b128 v[220:223], v107 offset:3072
	global_load_lds_dwordx4 v[62:63], off
	v_lshl_add_u64 v[62:63], v[2:3], 0, s[12:13]
	s_mov_b32 m0, s73
	s_nop 0
	global_load_lds_dwordx4 v[62:63], off
	s_barrier
	s_waitcnt lgkmcnt(0)
	v_mfma_f32_16x16x32_bf16 v[120:123], v[208:211], v[152:155], v[120:123]
	v_mfma_f32_16x16x32_bf16 v[22:25], v[216:219], v[152:155], v[22:25]
	v_mfma_f32_16x16x32_bf16 v[124:127], v[208:211], v[184:187], v[124:127]
	v_mfma_f32_16x16x32_bf16 v[26:29], v[216:219], v[184:187], v[26:29]
	v_mfma_f32_16x16x32_bf16 v[30:33], v[208:211], v[192:195], v[30:33]
	v_mfma_f32_16x16x32_bf16 v[34:37], v[216:219], v[192:195], v[34:37]
	v_mfma_f32_16x16x32_bf16 v[38:41], v[208:211], v[200:203], v[38:41]
	v_mfma_f32_16x16x32_bf16 v[42:45], v[216:219], v[200:203], v[42:45]
	v_mfma_f32_16x16x32_bf16 v[120:123], v[212:215], v[180:183], v[120:123]
	v_mfma_f32_16x16x32_bf16 v[22:25], v[220:223], v[180:183], v[22:25]
	v_mfma_f32_16x16x32_bf16 v[124:127], v[212:215], v[188:191], v[124:127]
	v_mfma_f32_16x16x32_bf16 v[26:29], v[220:223], v[188:191], v[26:29]
	v_mfma_f32_16x16x32_bf16 v[30:33], v[212:215], v[196:199], v[30:33]
	v_mfma_f32_16x16x32_bf16 v[34:37], v[220:223], v[196:199], v[34:37]
	v_mfma_f32_16x16x32_bf16 v[38:41], v[212:215], v[204:207], v[38:41]
	v_mfma_f32_16x16x32_bf16 v[42:45], v[220:223], v[204:207], v[42:45]
	s_mov_b32 m0, s38
	v_lshl_add_u64 v[62:63], v[4:5], 0, s[12:13]
	s_barrier
; #define PG8_STAGE(bufoff, gbase, voff) do { _Pragma("unroll") for (int _i = 0; _i < 2; ++_i) \
;         __builtin_amdgcn_global_load_lds((const unsigned*)((const char*)(gbase) + (voff)[_i]), (PG8_LAS unsigned*)(lds + (bufoff) + ldsw + _i * 8192), 16, 0, 0); } while (0)
; #define PG8_LDA(dst, b, h) do { _Pragma("unroll") for (int m = 0; m < 4; ++m) _Pragma("unroll") for (int k = 0; k < 2; ++k) dst[m][k] = *(const PG8_LAS bf16x8*)(lds + PG8_SA(b, h) + aoff + m * 2048 + k * 1024); } while (0)
; #define PG8_LDB(dst, b, h) do { _Pragma("unroll") for (int n = 0; n < 2; ++n) _Pragma("unroll") for (int k = 0; k < 2; ++k) dst[n][k] = *(const PG8_LAS bf16x8*)(lds + PG8_SB(b, h) + boff + n * 2048 + k * 1024); } while (0)
; #define PG8_WAIT_V(n) asm volatile("s_waitcnt vmcnt(" #n ")" ::: "memory")
; #define PG8_WAIT_L(n) asm volatile("s_waitcnt lgkmcnt(" #n ")" ::: "memory")
; #define PG8_BAR __builtin_amdgcn_s_barrier()
; #define PG8_SCHED __builtin_amdgcn_sched_barrier(0)
; template <class Epi, class Sched>
; __device__ __forceinline__ void gemm_phase(PG8_LAS unsigned char* lds, const Gemm g, const Sched& S, const Epi& E) {
;     ...
;             PG8_LDB(B0, 0, 0); PG8_SCHED; PG8_LDA(At, 0, 0); PG8_STAGE(PG8_SA(1, 1), a1 + hstep, voffA);
;             PG8_WAIT_L(8); PG8_BAR; PG8_WAIT_L(0); PG8_MMA(0, 0, At, B0); PG8_BAR; PG8_SCHED;
;             PG8_LDB(B1, 0, 1); PG8_STAGE(PG8_SB(0, 0), b2, voffB);
;             PG8_BAR; PG8_WAIT_L(0); PG8_MMA(0, 1, At, B1); PG8_BAR;
;             PG8_LDA(At, 0, 1); PG8_STAGE(PG8_SA(0, 0), a2, voffA);
;             PG8_BAR; PG8_WAIT_L(0); PG8_MMA(1, 0, At, B0); PG8_BAR; PG8_SCHED;
;             PG8_STAGE(PG8_SB(0, 1), b2 + hstep, voffB);
;             PG8_WAIT_V(6); PG8_BAR; PG8_MMA(1, 1, At, B1); PG8_BAR;
;             PG8_LDB(B0, 1, 0); PG8_SCHED; PG8_LDA(At, 1, 0); PG8_STAGE(PG8_SA(0, 1), a2 + hstep, voffA);
;             PG8_WAIT_L(8); PG8_BAR; PG8_WAIT_L(0); PG8_MMA(0, 0, At, B0); PG8_BAR; PG8_SCHED;
;             PG8_LDB(B1, 1, 1); PG8_STAGE(PG8_SB(1, 0), b3, voffB);
;             PG8_BAR; PG8_WAIT_L(0); PG8_MMA(0, 1, At, B1); PG8_BAR;
;             PG8_LDA(At, 1, 1); PG8_STAGE(PG8_SA(1, 0), a3, voffA);
;             PG8_BAR; PG8_WAIT_L(0); PG8_MMA(1, 0, At, B0); PG8_BAR; PG8_SCHED;
;             PG8_STAGE(PG8_SB(1, 1), b3 + hstep, voffB);
;             PG8_WAIT_V(6); PG8_BAR; PG8_MMA(1, 1, At, B1); PG8_BAR;
	ds_read_b128 v[152:155], v105 offset:16384
	ds_read_b128 v[180:183], v105 offset:17408
	ds_read_b128 v[184:187], v105 offset:18432
	ds_read_b128 v[188:191], v105 offset:19456
	ds_read_b128 v[192:195], v105 offset:20480
	ds_read_b128 v[196:199], v105 offset:21504
	ds_read_b128 v[200:203], v105 offset:22528
	ds_read_b128 v[204:207], v105 offset:23552
	global_load_lds_dwordx4 v[62:63], off
	v_lshl_add_u64 v[62:63], v[6:7], 0, s[12:13]
	s_mov_b32 m0, s39
	s_nop 0
	global_load_lds_dwordx4 v[62:63], off
	s_barrier
	s_waitcnt lgkmcnt(0)
	v_mfma_f32_16x16x32_bf16 v[156:159], v[136:139], v[152:155], v[156:159]
	v_mfma_f32_16x16x32_bf16 v[160:163], v[144:147], v[152:155], v[160:163]
	v_mfma_f32_16x16x32_bf16 v[164:167], v[136:139], v[184:187], v[164:167]
	v_mfma_f32_16x16x32_bf16 v[168:171], v[144:147], v[184:187], v[168:171]
	v_mfma_f32_16x16x32_bf16 v[172:175], v[136:139], v[192:195], v[172:175]
	v_mfma_f32_16x16x32_bf16 v[176:179], v[144:147], v[192:195], v[176:179]
	v_mfma_f32_16x16x32_bf16 v[10:13], v[136:139], v[200:203], v[10:13]
	v_mfma_f32_16x16x32_bf16 v[14:17], v[144:147], v[200:203], v[14:17]
	v_mfma_f32_16x16x32_bf16 v[156:159], v[140:143], v[180:183], v[156:159]
	v_mfma_f32_16x16x32_bf16 v[160:163], v[148:151], v[180:183], v[160:163]
	v_mfma_f32_16x16x32_bf16 v[164:167], v[140:143], v[188:191], v[164:167]
	v_mfma_f32_16x16x32_bf16 v[168:171], v[148:151], v[188:191], v[168:171]
	v_mfma_f32_16x16x32_bf16 v[172:175], v[140:143], v[196:199], v[172:175]
	v_mfma_f32_16x16x32_bf16 v[176:179], v[148:151], v[196:199], v[176:179]
	v_mfma_f32_16x16x32_bf16 v[10:13], v[140:143], v[204:207], v[10:13]
	v_mfma_f32_16x16x32_bf16 v[14:17], v[148:151], v[204:207], v[14:17]
	s_barrier
	s_add_u32 s82, s26, 0x18200
	s_addc_u32 s83, s27, 0
	s_mov_b32 m0, s76
	v_lshl_add_u64 v[62:63], s[82:83], 0, v[66:67]
	global_load_lds_dwordx4 v[62:63], off
	v_lshl_add_u64 v[62:63], s[82:83], 0, v[70:71]
	s_mov_b32 m0, s74
	s_nop 0
	global_load_lds_dwordx4 v[62:63], off
	s_waitcnt vmcnt(6)
	s_barrier
	v_mfma_f32_16x16x32_bf16 v[18:21], v[208:211], v[152:155], v[18:21]
	v_mfma_f32_16x16x32_bf16 v[46:49], v[216:219], v[152:155], v[46:49]
	v_mfma_f32_16x16x32_bf16 v[112:115], v[208:211], v[184:187], v[112:115]
	v_mfma_f32_16x16x32_bf16 v[116:119], v[216:219], v[184:187], v[116:119]
	v_mfma_f32_16x16x32_bf16 v[128:131], v[208:211], v[192:195], v[128:131]
	v_mfma_f32_16x16x32_bf16 v[132:135], v[216:219], v[192:195], v[132:135]
	v_mfma_f32_16x16x32_bf16 v[98:101], v[208:211], v[200:203], v[98:101]
	v_mfma_f32_16x16x32_bf16 v[108:111], v[216:219], v[200:203], v[108:111]
	v_mfma_f32_16x16x32_bf16 v[18:21], v[212:215], v[180:183], v[18:21]
	v_mfma_f32_16x16x32_bf16 v[46:49], v[220:223], v[180:183], v[46:49]
	v_mfma_f32_16x16x32_bf16 v[112:115], v[212:215], v[188:191], v[112:115]
	v_mfma_f32_16x16x32_bf16 v[116:119], v[220:223], v[188:191], v[116:119]
	v_mfma_f32_16x16x32_bf16 v[128:131], v[212:215], v[196:199], v[128:131]
	v_mfma_f32_16x16x32_bf16 v[132:135], v[220:223], v[196:199], v[132:135]
	v_mfma_f32_16x16x32_bf16 v[98:101], v[212:215], v[204:207], v[98:101]
	v_mfma_f32_16x16x32_bf16 v[108:111], v[220:223], v[204:207], v[108:111]
	s_barrier
	ds_read_b128 v[136:139], v8
	ds_read_b128 v[140:143], v8 offset:1024
	ds_read_b128 v[144:147], v8 offset:2048
	ds_read_b128 v[148:151], v8 offset:3072
	s_add_u32 s82, s24, 0x18200
	s_addc_u32 s83, s25, 0
	s_mov_b32 m0, s40
	v_lshl_add_u64 v[62:63], s[82:83], 0, v[64:65]
	ds_read_b128 v[152:155], v105 offset:32768
	ds_read_b128 v[180:183], v105 offset:33792
	ds_read_b128 v[184:187], v105 offset:34816
	ds_read_b128 v[188:191], v105 offset:35840
	ds_read_b128 v[192:195], v105 offset:36864
	ds_read_b128 v[196:199], v105 offset:37888
	ds_read_b128 v[200:203], v105 offset:38912
	ds_read_b128 v[204:207], v105 offset:39936
	global_load_lds_dwordx4 v[62:63], off
	v_lshl_add_u64 v[62:63], s[82:83], 0, v[68:69]
	s_mov_b32 m0, s41
	s_nop 0
	global_load_lds_dwordx4 v[62:63], off
	s_waitcnt lgkmcnt(8)
	s_barrier
	s_waitcnt lgkmcnt(0)
	v_mfma_f32_16x16x32_bf16 v[50:53], v[136:139], v[152:155], v[50:53]
	v_mfma_f32_16x16x32_bf16 v[54:57], v[144:147], v[152:155], v[54:57]
	v_mfma_f32_16x16x32_bf16 v[58:61], v[136:139], v[184:187], v[58:61]
	v_mfma_f32_16x16x32_bf16 v[78:81], v[144:147], v[184:187], v[78:81]
	v_mfma_f32_16x16x32_bf16 v[82:85], v[136:139], v[192:195], v[82:85]
	v_mfma_f32_16x16x32_bf16 v[86:89], v[144:147], v[192:195], v[86:89]
	v_mfma_f32_16x16x32_bf16 v[90:93], v[136:139], v[200:203], v[90:93]
	v_mfma_f32_16x16x32_bf16 v[94:97], v[144:147], v[200:203], v[94:97]
	v_mfma_f32_16x16x32_bf16 v[50:53], v[140:143], v[180:183], v[50:53]
	v_mfma_f32_16x16x32_bf16 v[54:57], v[148:151], v[180:183], v[54:57]
	v_mfma_f32_16x16x32_bf16 v[58:61], v[140:143], v[188:191], v[58:61]
	v_mfma_f32_16x16x32_bf16 v[78:81], v[148:151], v[188:191], v[78:81]
	v_mfma_f32_16x16x32_bf16 v[82:85], v[140:143], v[196:199], v[82:85]
	v_mfma_f32_16x16x32_bf16 v[86:89], v[148:151], v[196:199], v[86:89]
	v_mfma_f32_16x16x32_bf16 v[90:93], v[140:143], v[204:207], v[90:93]
	v_mfma_f32_16x16x32_bf16 v[94:97], v[148:151], v[204:207], v[94:97]
	s_barrier
	s_mov_b32 m0, s80
	v_lshl_add_u64 v[0:1], v[0:1], 0, s[18:19]
	ds_read_b128 v[208:211], v9
	ds_read_b128 v[212:215], v9 offset:1024
	ds_read_b128 v[216:219], v9 offset:2048
	ds_read_b128 v[220:223], v9 offset:3072
	global_load_lds_dwordx4 v[0:1], off
	v_lshl_add_u64 v[0:1], v[2:3], 0, s[18:19]
	s_mov_b32 m0, s77
	s_nop 0
	global_load_lds_dwordx4 v[0:1], off
	s_barrier
; #define PG8_STAGE(bufoff, gbase, voff) do { _Pragma("unroll") for (int _i = 0; _i < 2; ++_i) \
;         __builtin_amdgcn_global_load_lds((const unsigned*)((const char*)(gbase) + (voff)[_i]), (PG8_LAS unsigned*)(lds + (bufoff) + ldsw + _i * 8192), 16, 0, 0); } while (0)
; #define PG8_LDA(dst, b, h) do { _Pragma("unroll") for (int m = 0; m < 4; ++m) _Pragma("unroll") for (int k = 0; k < 2; ++k) dst[m][k] = *(const PG8_LAS bf16x8*)(lds + PG8_SA(b, h) + aoff + m * 2048 + k * 1024); } while (0)
; #define PG8_LDB(dst, b, h) do { _Pragma("unroll") for (int n = 0; n < 2; ++n) _Pragma("unroll") for (int k = 0; k < 2; ++k) dst[n][k] = *(const PG8_LAS bf16x8*)(lds + PG8_SB(b, h) + boff + n * 2048 + k * 1024); } while (0)
; #define PG8_WAIT_V(n) asm volatile("s_waitcnt vmcnt(" #n ")" ::: "memory")
; #define PG8_WAIT_L(n) asm volatile("s_waitcnt lgkmcnt(" #n ")" ::: "memory")
; #define PG8_BAR __builtin_amdgcn_s_barrier()
; #define PG8_SCHED __builtin_amdgcn_sched_barrier(0)
; template <class Epi, class Sched>
; __device__ __forceinline__ void gemm_phase(PG8_LAS unsigned char* lds, const Gemm g, const Sched& S, const Epi& E) {
;     ...
;             PG8_LDB(B0, 0, 0); PG8_SCHED; PG8_LDA(At, 0, 0); PG8_STAGE(PG8_SA(1, 1), a1 + hstep, voffA);
;             PG8_WAIT_L(8); PG8_BAR; PG8_WAIT_L(0); PG8_MMA(0, 0, At, B0); PG8_BAR; PG8_SCHED;
;             PG8_LDB(B1, 0, 1); PG8_STAGE(PG8_SB(0, 0), b2, voffB);
;             PG8_BAR; PG8_WAIT_L(0); PG8_MMA(0, 1, At, B1); PG8_BAR;
;             PG8_LDA(At, 0, 1); PG8_STAGE(PG8_SA(0, 0), a2, voffA);
;             PG8_BAR; PG8_WAIT_L(0); PG8_MMA(1, 0, At, B0); PG8_BAR; PG8_SCHED;
;             PG8_STAGE(PG8_SB(0, 1), b2 + hstep, voffB);
;             PG8_WAIT_V(6); PG8_BAR; PG8_MMA(1, 1, At, B1); PG8_BAR;
;             PG8_LDB(B0, 1, 0); PG8_SCHED; PG8_LDA(At, 1, 0); PG8_STAGE(PG8_SA(0, 1), a2 + hstep, voffA);
;             PG8_WAIT_L(8); PG8_BAR; PG8_WAIT_L(0); PG8_MMA(0, 0, At, B0); PG8_BAR; PG8_SCHED;
;             PG8_LDB(B1, 1, 1); PG8_STAGE(PG8_SB(1, 0), b3, voffB);
;             PG8_BAR; PG8_WAIT_L(0); PG8_MMA(0, 1, At, B1); PG8_BAR;
;             PG8_LDA(At, 1, 1); PG8_STAGE(PG8_SA(1, 0), a3, voffA);
;             PG8_BAR; PG8_WAIT_L(0); PG8_MMA(1, 0, At, B0); PG8_BAR; PG8_SCHED;
;             PG8_STAGE(PG8_SB(1, 1), b3 + hstep, voffB);
;             PG8_WAIT_V(6); PG8_BAR; PG8_MMA(1, 1, At, B1); PG8_BAR;
	s_waitcnt lgkmcnt(0)
	v_mfma_f32_16x16x32_bf16 v[0:3], v[208:211], v[152:155], v[120:123]
	v_mfma_f32_16x16x32_bf16 v[22:25], v[216:219], v[152:155], v[22:25]
	v_mfma_f32_16x16x32_bf16 v[120:123], v[208:211], v[184:187], v[124:127]
	v_mfma_f32_16x16x32_bf16 v[26:29], v[216:219], v[184:187], v[26:29]
	v_mfma_f32_16x16x32_bf16 v[30:33], v[208:211], v[192:195], v[30:33]
	v_mfma_f32_16x16x32_bf16 v[34:37], v[216:219], v[192:195], v[34:37]
	v_mfma_f32_16x16x32_bf16 v[38:41], v[208:211], v[200:203], v[38:41]
	v_mfma_f32_16x16x32_bf16 v[42:45], v[216:219], v[200:203], v[42:45]
	v_mfma_f32_16x16x32_bf16 v[0:3], v[212:215], v[180:183], v[0:3]
	v_mfma_f32_16x16x32_bf16 v[22:25], v[220:223], v[180:183], v[22:25]
	v_mfma_f32_16x16x32_bf16 v[120:123], v[212:215], v[188:191], v[120:123]
	v_mfma_f32_16x16x32_bf16 v[26:29], v[220:223], v[188:191], v[26:29]
	v_mfma_f32_16x16x32_bf16 v[30:33], v[212:215], v[196:199], v[30:33]
	v_mfma_f32_16x16x32_bf16 v[34:37], v[220:223], v[196:199], v[34:37]
	v_mfma_f32_16x16x32_bf16 v[38:41], v[212:215], v[204:207], v[38:41]
	v_mfma_f32_16x16x32_bf16 v[42:45], v[220:223], v[204:207], v[42:45]
	s_mov_b32 m0, s43
	v_lshl_add_u64 v[4:5], v[4:5], 0, s[18:19]
	s_barrier
	ds_read_b128 v[124:127], v105 offset:49152
	ds_read_b128 v[152:155], v105 offset:50176
	ds_read_b128 v[180:183], v105 offset:51200
	ds_read_b128 v[184:187], v105 offset:52224
	ds_read_b128 v[188:191], v105 offset:53248
	ds_read_b128 v[192:195], v105 offset:54272
	ds_read_b128 v[196:199], v105 offset:55296
	ds_read_b128 v[200:203], v105 offset:56320
	global_load_lds_dwordx4 v[4:5], off
	v_lshl_add_u64 v[4:5], v[6:7], 0, s[18:19]
	s_mov_b32 m0, s60
	s_nop 0
	global_load_lds_dwordx4 v[4:5], off
	s_barrier
	s_waitcnt lgkmcnt(0)
	v_mfma_f32_16x16x32_bf16 v[4:7], v[136:139], v[124:127], v[156:159]
	v_mfma_f32_16x16x32_bf16 v[156:159], v[144:147], v[124:127], v[160:163]
	v_mfma_f32_16x16x32_bf16 v[160:163], v[136:139], v[180:183], v[164:167]
	v_mfma_f32_16x16x32_bf16 v[164:167], v[144:147], v[180:183], v[168:171]
	v_mfma_f32_16x16x32_bf16 v[168:171], v[136:139], v[188:191], v[172:175]
	v_mfma_f32_16x16x32_bf16 v[172:175], v[144:147], v[188:191], v[176:179]
	v_mfma_f32_16x16x32_bf16 v[10:13], v[136:139], v[196:199], v[10:13]
	v_mfma_f32_16x16x32_bf16 v[14:17], v[144:147], v[196:199], v[14:17]
	v_mfma_f32_16x16x32_bf16 v[4:7], v[140:143], v[152:155], v[4:7]
	v_mfma_f32_16x16x32_bf16 v[156:159], v[148:151], v[152:155], v[156:159]
	v_mfma_f32_16x16x32_bf16 v[160:163], v[140:143], v[184:187], v[160:163]
	v_mfma_f32_16x16x32_bf16 v[164:167], v[148:151], v[184:187], v[164:167]
	v_mfma_f32_16x16x32_bf16 v[168:171], v[140:143], v[192:195], v[168:171]
	v_mfma_f32_16x16x32_bf16 v[172:175], v[148:151], v[192:195], v[172:175]
	v_mfma_f32_16x16x32_bf16 v[10:13], v[140:143], v[200:203], v[10:13]
	v_mfma_f32_16x16x32_bf16 v[14:17], v[148:151], v[200:203], v[14:17]
	s_barrier
	s_add_u32 s26, s26, 0x18280
	s_addc_u32 s27, s27, 0
	s_mov_b32 m0, s81
	v_lshl_add_u64 v[62:63], s[26:27], 0, v[66:67]
	global_load_lds_dwordx4 v[62:63], off
	v_lshl_add_u64 v[62:63], s[26:27], 0, v[70:71]
	s_mov_b32 m0, s78
	s_nop 0
	global_load_lds_dwordx4 v[62:63], off
	s_waitcnt vmcnt(6)
	s_barrier
	v_mfma_f32_16x16x32_bf16 v[18:21], v[208:211], v[124:127], v[18:21]
	v_mfma_f32_16x16x32_bf16 v[46:49], v[216:219], v[124:127], v[46:49]
	v_mfma_f32_16x16x32_bf16 v[112:115], v[208:211], v[180:183], v[112:115]
	v_mfma_f32_16x16x32_bf16 v[116:119], v[216:219], v[180:183], v[116:119]
	v_mfma_f32_16x16x32_bf16 v[124:127], v[208:211], v[188:191], v[128:131]
	v_mfma_f32_16x16x32_bf16 v[128:131], v[216:219], v[188:191], v[132:135]
	v_mfma_f32_16x16x32_bf16 v[98:101], v[208:211], v[196:199], v[98:101]
	v_mfma_f32_16x16x32_bf16 v[108:111], v[216:219], v[196:199], v[108:111]
	v_mfma_f32_16x16x32_bf16 v[18:21], v[212:215], v[152:155], v[18:21]
	v_mfma_f32_16x16x32_bf16 v[46:49], v[220:223], v[152:155], v[46:49]
	v_mfma_f32_16x16x32_bf16 v[112:115], v[212:215], v[184:187], v[112:115]
	v_mfma_f32_16x16x32_bf16 v[116:119], v[220:223], v[184:187], v[116:119]
	v_mfma_f32_16x16x32_bf16 v[124:127], v[212:215], v[192:195], v[124:127]
	v_mfma_f32_16x16x32_bf16 v[128:131], v[220:223], v[192:195], v[128:131]
	v_mfma_f32_16x16x32_bf16 v[98:101], v[212:215], v[200:203], v[98:101]
	v_mfma_f32_16x16x32_bf16 v[108:111], v[220:223], v[200:203], v[108:111]
	s_barrier
	ds_read_b128 v[132:135], v106
	ds_read_b128 v[136:139], v106 offset:1024
	ds_read_b128 v[140:143], v106 offset:2048
	ds_read_b128 v[144:147], v106 offset:3072
	s_add_u32 s24, s24, 0x18280
	s_addc_u32 s25, s25, 0
	s_mov_b32 m0, s79
	v_lshl_add_u64 v[62:63], s[24:25], 0, v[64:65]
	ds_read_b128 v[148:151], v105
	ds_read_b128 v[152:155], v105 offset:1024
	ds_read_b128 v[176:179], v105 offset:2048
	ds_read_b128 v[180:183], v105 offset:3072
	ds_read_b128 v[184:187], v105 offset:4096
	ds_read_b128 v[188:191], v105 offset:5120
	ds_read_b128 v[192:195], v105 offset:6144
	ds_read_b128 v[196:199], v105 offset:7168
	global_load_lds_dwordx4 v[62:63], off
	v_lshl_add_u64 v[62:63], s[24:25], 0, v[68:69]
	s_mov_b32 m0, s72
	s_nop 0
	global_load_lds_dwordx4 v[62:63], off
	s_waitcnt lgkmcnt(8)
	s_barrier
; #define PG8_STAGE(bufoff, gbase, voff) do { _Pragma("unroll") for (int _i = 0; _i < 2; ++_i) \
;         __builtin_amdgcn_global_load_lds((const unsigned*)((const char*)(gbase) + (voff)[_i]), (PG8_LAS unsigned*)(lds + (bufoff) + ldsw + _i * 8192), 16, 0, 0); } while (0)
; #define PG8_LDA(dst, b, h) do { _Pragma("unroll") for (int m = 0; m < 4; ++m) _Pragma("unroll") for (int k = 0; k < 2; ++k) dst[m][k] = *(const PG8_LAS bf16x8*)(lds + PG8_SA(b, h) + aoff + m * 2048 + k * 1024); } while (0)
; #define PG8_LDB(dst, b, h) do { _Pragma("unroll") for (int n = 0; n < 2; ++n) _Pragma("unroll") for (int k = 0; k < 2; ++k) dst[n][k] = *(const PG8_LAS bf16x8*)(lds + PG8_SB(b, h) + boff + n * 2048 + k * 1024); } while (0)
; #define PG8_WAIT_V(n) asm volatile("s_waitcnt vmcnt(" #n ")" ::: "memory")
; #define PG8_WAIT_L(n) asm volatile("s_waitcnt lgkmcnt(" #n ")" ::: "memory")
; #define PG8_BAR __builtin_amdgcn_s_barrier()
; #define PG8_SCHED __builtin_amdgcn_sched_barrier(0)
; template <class Epi, class Sched>
; __device__ __forceinline__ void gemm_phase(PG8_LAS unsigned char* lds, const Gemm g, const Sched& S, const Epi& E) {
;     ...
;             PG8_LDB(B0, 0, 0); PG8_SCHED; PG8_LDA(At, 0, 0); PG8_STAGE(PG8_SA(1, 1), a1 + hstep, voffA);
;             PG8_WAIT_L(8); PG8_BAR; PG8_WAIT_L(0); PG8_MMA(0, 0, At, B0); PG8_BAR; PG8_SCHED;
;             PG8_LDB(B1, 0, 1); PG8_STAGE(PG8_SB(0, 0), b2, voffB);
;             PG8_BAR; PG8_WAIT_L(0); PG8_MMA(0, 1, At, B1); PG8_BAR;
;             PG8_LDA(At, 0, 1); PG8_STAGE(PG8_SA(0, 0), a2, voffA);
;             PG8_BAR; PG8_WAIT_L(0); PG8_MMA(1, 0, At, B0); PG8_BAR; PG8_SCHED;
;             PG8_STAGE(PG8_SB(0, 1), b2 + hstep, voffB);
;             PG8_WAIT_V(6); PG8_BAR; PG8_MMA(1, 1, At, B1); PG8_BAR;
;             PG8_LDB(B0, 1, 0); PG8_SCHED; PG8_LDA(At, 1, 0); PG8_STAGE(PG8_SA(0, 1), a2 + hstep, voffA);
;             PG8_WAIT_L(8); PG8_BAR; PG8_WAIT_L(0); PG8_MMA(0, 0, At, B0); PG8_BAR; PG8_SCHED;
;             PG8_LDB(B1, 1, 1); PG8_STAGE(PG8_SB(1, 0), b3, voffB);
;             PG8_BAR; PG8_WAIT_L(0); PG8_MMA(0, 1, At, B1); PG8_BAR;
;             PG8_LDA(At, 1, 1); PG8_STAGE(PG8_SA(1, 0), a3, voffA);
;             PG8_BAR; PG8_WAIT_L(0); PG8_MMA(1, 0, At, B0); PG8_BAR; PG8_SCHED;
;             PG8_STAGE(PG8_SB(1, 1), b3 + hstep, voffB);
;             PG8_WAIT_V(6); PG8_BAR; PG8_MMA(1, 1, At, B1); PG8_BAR;
	s_waitcnt lgkmcnt(0)
	v_mfma_f32_16x16x32_bf16 v[58:61], v[132:135], v[176:179], v[58:61]
	v_mfma_f32_16x16x32_bf16 v[200:203], v[136:139], v[180:183], v[58:61]
	v_mfma_f32_16x16x32_bf16 v[58:61], v[140:143], v[176:179], v[78:81]
	v_mfma_f32_16x16x32_bf16 v[78:81], v[144:147], v[180:183], v[58:61]
	v_mfma_f32_16x16x32_bf16 v[58:61], v[132:135], v[184:187], v[82:85]
	v_mfma_f32_16x16x32_bf16 v[82:85], v[136:139], v[188:191], v[58:61]
	v_mfma_f32_16x16x32_bf16 v[58:61], v[140:143], v[184:187], v[86:89]
	v_mfma_f32_16x16x32_bf16 v[86:89], v[144:147], v[188:191], v[58:61]
	v_mfma_f32_16x16x32_bf16 v[58:61], v[132:135], v[192:195], v[90:93]
	v_mfma_f32_16x16x32_bf16 v[50:53], v[132:135], v[148:151], v[50:53]
	v_mfma_f32_16x16x32_bf16 v[54:57], v[140:143], v[148:151], v[54:57]
	v_mfma_f32_16x16x32_bf16 v[90:93], v[136:139], v[196:199], v[58:61]
	v_mfma_f32_16x16x32_bf16 v[58:61], v[140:143], v[192:195], v[94:97]
	v_mfma_f32_16x16x32_bf16 v[50:53], v[136:139], v[152:155], v[50:53]
	v_mfma_f32_16x16x32_bf16 v[54:57], v[144:147], v[152:155], v[54:57]
	v_mfma_f32_16x16x32_bf16 v[94:97], v[144:147], v[196:199], v[58:61]
	s_barrier
	s_mov_b32 m0, s75
	v_lshl_add_u64 v[224:225], s[8:9], 0, v[66:67]
	s_nop 0
	ds_read_b128 v[58:61], v107
	ds_read_b128 v[204:207], v107 offset:1024
	ds_read_b128 v[208:211], v107 offset:2048
	ds_read_b128 v[212:215], v107 offset:3072
	global_load_lds_dwordx4 v[224:225], off
	v_lshl_add_u64 v[226:227], s[8:9], 0, v[70:71]
	s_mov_b32 m0, s73
	s_nop 0
	global_load_lds_dwordx4 v[226:227], off
	s_barrier
	s_waitcnt lgkmcnt(0)
	v_mfma_f32_16x16x32_bf16 v[30:33], v[58:61], v[184:187], v[30:33]
	v_mfma_f32_16x16x32_bf16 v[0:3], v[58:61], v[148:151], v[0:3]
	v_mfma_f32_16x16x32_bf16 v[22:25], v[208:211], v[148:151], v[22:25]
	v_mfma_f32_16x16x32_bf16 v[148:151], v[204:207], v[188:191], v[30:33]
	v_mfma_f32_16x16x32_bf16 v[30:33], v[208:211], v[184:187], v[34:37]
	v_mfma_f32_16x16x32_bf16 v[0:3], v[204:207], v[152:155], v[0:3]
	v_mfma_f32_16x16x32_bf16 v[22:25], v[212:215], v[152:155], v[22:25]
	v_mfma_f32_16x16x32_bf16 v[152:155], v[212:215], v[188:191], v[30:33]
	v_mfma_f32_16x16x32_bf16 v[30:33], v[58:61], v[192:195], v[38:41]
	v_mfma_f32_16x16x32_bf16 v[120:123], v[58:61], v[176:179], v[120:123]
	v_mfma_f32_16x16x32_bf16 v[26:29], v[208:211], v[176:179], v[26:29]
	v_mfma_f32_16x16x32_bf16 v[176:179], v[204:207], v[196:199], v[30:33]
	v_mfma_f32_16x16x32_bf16 v[30:33], v[208:211], v[192:195], v[42:45]
	v_mfma_f32_16x16x32_bf16 v[120:123], v[204:207], v[180:183], v[120:123]
	v_mfma_f32_16x16x32_bf16 v[26:29], v[212:215], v[180:183], v[26:29]
	v_mfma_f32_16x16x32_bf16 v[180:183], v[212:215], v[196:199], v[30:33]
	s_mov_b32 m0, s38
	v_lshl_add_u64 v[240:241], s[0:1], 0, v[64:65]
	s_barrier
	s_nop 0
	ds_read_b128 v[30:33], v105 offset:16384
	ds_read_b128 v[34:37], v105 offset:17408
	ds_read_b128 v[38:41], v105 offset:18432
	ds_read_b128 v[42:45], v105 offset:19456
	ds_read_b128 v[184:187], v105 offset:20480
	ds_read_b128 v[188:191], v105 offset:21504
	ds_read_b128 v[192:195], v105 offset:22528
	ds_read_b128 v[196:199], v105 offset:23552
	global_load_lds_dwordx4 v[240:241], off
	v_lshl_add_u64 v[242:243], s[0:1], 0, v[68:69]
	s_mov_b32 m0, s39
	s_nop 0
	global_load_lds_dwordx4 v[242:243], off
	s_barrier
	s_waitcnt lgkmcnt(0)
	v_mfma_f32_16x16x32_bf16 v[10:13], v[132:135], v[192:195], v[10:13]
	v_mfma_f32_16x16x32_bf16 v[4:7], v[132:135], v[30:33], v[4:7]
	v_mfma_f32_16x16x32_bf16 v[156:159], v[140:143], v[30:33], v[156:159]
	v_mfma_f32_16x16x32_bf16 v[160:163], v[132:135], v[38:41], v[160:163]
	v_mfma_f32_16x16x32_bf16 v[164:167], v[140:143], v[38:41], v[164:167]
	v_mfma_f32_16x16x32_bf16 v[168:171], v[132:135], v[184:187], v[168:171]
	v_mfma_f32_16x16x32_bf16 v[172:175], v[140:143], v[184:187], v[172:175]
	v_mfma_f32_16x16x32_bf16 v[132:135], v[136:139], v[196:199], v[10:13]
	v_mfma_f32_16x16x32_bf16 v[10:13], v[140:143], v[192:195], v[14:17]
	v_mfma_f32_16x16x32_bf16 v[4:7], v[136:139], v[34:37], v[4:7]
	v_mfma_f32_16x16x32_bf16 v[156:159], v[144:147], v[34:37], v[156:159]
	v_mfma_f32_16x16x32_bf16 v[160:163], v[136:139], v[42:45], v[160:163]
	v_mfma_f32_16x16x32_bf16 v[164:167], v[144:147], v[42:45], v[164:167]
	v_mfma_f32_16x16x32_bf16 v[168:171], v[136:139], v[188:191], v[168:171]
	v_mfma_f32_16x16x32_bf16 v[172:175], v[144:147], v[188:191], v[172:175]
	v_mfma_f32_16x16x32_bf16 v[136:139], v[144:147], v[196:199], v[10:13]
	s_barrier
	s_add_u32 s24, s8, 0x18000
	s_addc_u32 s25, s9, 0
	s_mov_b32 m0, s76
	v_lshl_add_u64 v[10:11], s[24:25], 0, v[66:67]
	global_load_lds_dwordx4 v[10:11], off
	v_lshl_add_u64 v[10:11], s[24:25], 0, v[70:71]
	s_mov_b32 m0, s74
	s_nop 0
	global_load_lds_dwordx4 v[10:11], off
	s_waitcnt vmcnt(6)
	s_barrier
	v_mfma_f32_16x16x32_bf16 v[10:13], v[58:61], v[30:33], v[18:21]
	v_mfma_f32_16x16x32_bf16 v[140:143], v[204:207], v[34:37], v[10:13]
	v_mfma_f32_16x16x32_bf16 v[10:13], v[208:211], v[30:33], v[46:49]
	v_mfma_f32_16x16x32_bf16 v[144:147], v[212:215], v[34:37], v[10:13]
	v_mfma_f32_16x16x32_bf16 v[10:13], v[58:61], v[38:41], v[112:115]
	v_mfma_f32_16x16x32_bf16 v[112:115], v[204:207], v[42:45], v[10:13]
	v_mfma_f32_16x16x32_bf16 v[10:13], v[208:211], v[38:41], v[116:119]
	v_mfma_f32_16x16x32_bf16 v[116:119], v[212:215], v[42:45], v[10:13]
	v_mfma_f32_16x16x32_bf16 v[10:13], v[58:61], v[184:187], v[124:127]
	v_mfma_f32_16x16x32_bf16 v[124:127], v[204:207], v[188:191], v[10:13]
	v_mfma_f32_16x16x32_bf16 v[10:13], v[208:211], v[184:187], v[128:131]
	v_mfma_f32_16x16x32_bf16 v[128:131], v[212:215], v[188:191], v[10:13]
	v_mfma_f32_16x16x32_bf16 v[10:13], v[58:61], v[192:195], v[98:101]
	v_mfma_f32_16x16x32_bf16 v[98:101], v[204:207], v[196:199], v[10:13]
	v_mfma_f32_16x16x32_bf16 v[10:13], v[208:211], v[192:195], v[108:111]
	v_mfma_f32_16x16x32_bf16 v[108:111], v[212:215], v[196:199], v[10:13]
	s_barrier
; #define PG8_STAGE(bufoff, gbase, voff) do { _Pragma("unroll") for (int _i = 0; _i < 2; ++_i) \
;         __builtin_amdgcn_global_load_lds((const unsigned*)((const char*)(gbase) + (voff)[_i]), (PG8_LAS unsigned*)(lds + (bufoff) + ldsw + _i * 8192), 16, 0, 0); } while (0)
; #define PG8_LDA(dst, b, h) do { _Pragma("unroll") for (int m = 0; m < 4; ++m) _Pragma("unroll") for (int k = 0; k < 2; ++k) dst[m][k] = *(const PG8_LAS bf16x8*)(lds + PG8_SA(b, h) + aoff + m * 2048 + k * 1024); } while (0)
; #define PG8_LDB(dst, b, h) do { _Pragma("unroll") for (int n = 0; n < 2; ++n) _Pragma("unroll") for (int k = 0; k < 2; ++k) dst[n][k] = *(const PG8_LAS bf16x8*)(lds + PG8_SB(b, h) + boff + n * 2048 + k * 1024); } while (0)
; #define PG8_WAIT_V(n) asm volatile("s_waitcnt vmcnt(" #n ")" ::: "memory")
; #define PG8_WAIT_L(n) asm volatile("s_waitcnt lgkmcnt(" #n ")" ::: "memory")
; #define PG8_BAR __builtin_amdgcn_s_barrier()
; #define PG8_SCHED __builtin_amdgcn_sched_barrier(0)
; template <class Epi, class Sched>
; __device__ __forceinline__ void gemm_phase(PG8_LAS unsigned char* lds, const Gemm g, const Sched& S, const Epi& E) {
;     ...
;             PG8_LDB(B0, 0, 0); PG8_SCHED; PG8_LDA(At, 0, 0); PG8_STAGE(PG8_SA(1, 1), a1 + hstep, voffA);
;             PG8_WAIT_L(8); PG8_BAR; PG8_WAIT_L(0); PG8_MMA(0, 0, At, B0); PG8_BAR; PG8_SCHED;
;             PG8_LDB(B1, 0, 1); PG8_STAGE(PG8_SB(0, 0), b2, voffB);
;             PG8_BAR; PG8_WAIT_L(0); PG8_MMA(0, 1, At, B1); PG8_BAR;
;             PG8_LDA(At, 0, 1); PG8_STAGE(PG8_SA(0, 0), a2, voffA);
;             PG8_BAR; PG8_WAIT_L(0); PG8_MMA(1, 0, At, B0); PG8_BAR; PG8_SCHED;
;             PG8_STAGE(PG8_SB(0, 1), b2 + hstep, voffB);
;             PG8_WAIT_V(6); PG8_BAR; PG8_MMA(1, 1, At, B1); PG8_BAR;
;             PG8_LDB(B0, 1, 0); PG8_SCHED; PG8_LDA(At, 1, 0); PG8_STAGE(PG8_SA(0, 1), a2 + hstep, voffA);
;             PG8_WAIT_L(8); PG8_BAR; PG8_WAIT_L(0); PG8_MMA(0, 0, At, B0); PG8_BAR; PG8_SCHED;
;             PG8_LDB(B1, 1, 1); PG8_STAGE(PG8_SB(1, 0), b3, voffB);
;             PG8_BAR; PG8_WAIT_L(0); PG8_MMA(0, 1, At, B1); PG8_BAR;
;             PG8_LDA(At, 1, 1); PG8_STAGE(PG8_SA(1, 0), a3, voffA);
;             PG8_BAR; PG8_WAIT_L(0); PG8_MMA(1, 0, At, B0); PG8_BAR; PG8_SCHED;
;             PG8_STAGE(PG8_SB(1, 1), b3 + hstep, voffB);
;             PG8_WAIT_V(6); PG8_BAR; PG8_MMA(1, 1, At, B1); PG8_BAR;
	ds_read_b128 v[184:187], v8
	ds_read_b128 v[188:191], v8 offset:1024
	ds_read_b128 v[192:195], v8 offset:2048
	ds_read_b128 v[196:199], v8 offset:3072
	s_add_u32 s24, s0, 0x18000
	s_addc_u32 s25, s1, 0
	s_mov_b32 m0, s40
	v_lshl_add_u64 v[30:31], s[24:25], 0, v[64:65]
	ds_read_b128 v[10:13], v105 offset:32768
	ds_read_b128 v[14:17], v105 offset:33792
	ds_read_b128 v[18:21], v105 offset:34816
	ds_read_b128 v[204:207], v105 offset:35840
	ds_read_b128 v[208:211], v105 offset:36864
	ds_read_b128 v[212:215], v105 offset:37888
	ds_read_b128 v[216:219], v105 offset:38912
	ds_read_b128 v[220:223], v105 offset:39936
	global_load_lds_dwordx4 v[30:31], off
	v_lshl_add_u64 v[30:31], s[24:25], 0, v[68:69]
	s_mov_b32 m0, s41
	s_nop 0
	global_load_lds_dwordx4 v[30:31], off
	s_waitcnt lgkmcnt(8)
	s_barrier
	s_waitcnt lgkmcnt(0)
	v_mfma_f32_16x16x32_bf16 v[30:33], v[184:187], v[10:13], v[50:53]
	v_mfma_f32_16x16x32_bf16 v[60:63], v[188:191], v[14:17], v[30:33]
	v_mfma_f32_16x16x32_bf16 v[30:33], v[192:195], v[10:13], v[54:57]
	v_mfma_f32_16x16x32_bf16 v[56:59], v[196:199], v[14:17], v[30:33]
	v_mfma_f32_16x16x32_bf16 v[30:33], v[184:187], v[18:21], v[200:203]
	v_mfma_f32_16x16x32_bf16 v[48:51], v[188:191], v[204:207], v[30:33]
	v_mfma_f32_16x16x32_bf16 v[30:33], v[192:195], v[18:21], v[78:81]
	v_mfma_f32_16x16x32_bf16 v[52:55], v[196:199], v[204:207], v[30:33]
	v_mfma_f32_16x16x32_bf16 v[30:33], v[184:187], v[208:211], v[82:85]
	v_mfma_f32_16x16x32_bf16 v[40:43], v[188:191], v[212:215], v[30:33]
	v_mfma_f32_16x16x32_bf16 v[30:33], v[192:195], v[208:211], v[86:89]
	v_mfma_f32_16x16x32_bf16 v[44:47], v[196:199], v[212:215], v[30:33]
	v_mfma_f32_16x16x32_bf16 v[30:33], v[184:187], v[216:219], v[90:93]
	v_mfma_f32_16x16x32_bf16 v[36:39], v[192:195], v[216:219], v[94:97]
	v_mfma_f32_16x16x32_bf16 v[32:35], v[188:191], v[220:223], v[30:33]
	v_mfma_f32_16x16x32_bf16 v[36:39], v[196:199], v[220:223], v[36:39]
	s_barrier
	s_mov_b32 m0, s80
	ds_read_b128 v[78:81], v9
	ds_read_b128 v[82:85], v9 offset:1024
	ds_read_b128 v[86:89], v9 offset:2048
	ds_read_b128 v[90:93], v9 offset:3072
	v_lshl_add_u64 v[8:9], v[224:225], 0, s[10:11]
	global_load_lds_dwordx4 v[8:9], off
	v_lshl_add_u64 v[8:9], v[226:227], 0, s[10:11]
	s_mov_b32 m0, s77
	s_nop 0
	global_load_lds_dwordx4 v[8:9], off
	s_barrier
	s_waitcnt lgkmcnt(0)
	v_mfma_f32_16x16x32_bf16 v[0:3], v[78:81], v[10:13], v[0:3]
	v_mfma_f32_16x16x32_bf16 v[94:97], v[82:85], v[14:17], v[0:3]
	v_mfma_f32_16x16x32_bf16 v[0:3], v[86:89], v[10:13], v[22:25]
	v_mfma_f32_16x16x32_bf16 v[200:203], v[90:93], v[14:17], v[0:3]
	v_mfma_f32_16x16x32_bf16 v[0:3], v[78:81], v[18:21], v[120:123]
	v_mfma_f32_16x16x32_bf16 v[120:123], v[82:85], v[204:207], v[0:3]
	v_mfma_f32_16x16x32_bf16 v[0:3], v[86:89], v[18:21], v[26:29]
	v_mfma_f32_16x16x32_bf16 v[204:207], v[90:93], v[204:207], v[0:3]
	v_mfma_f32_16x16x32_bf16 v[0:3], v[78:81], v[208:211], v[148:151]
	v_mfma_f32_16x16x32_bf16 v[148:151], v[82:85], v[212:215], v[0:3]
	v_mfma_f32_16x16x32_bf16 v[0:3], v[86:89], v[208:211], v[152:155]
	v_mfma_f32_16x16x32_bf16 v[152:155], v[90:93], v[212:215], v[0:3]
	v_mfma_f32_16x16x32_bf16 v[0:3], v[78:81], v[216:219], v[176:179]
	v_mfma_f32_16x16x32_bf16 v[176:179], v[82:85], v[220:223], v[0:3]
	v_mfma_f32_16x16x32_bf16 v[0:3], v[86:89], v[216:219], v[180:183]
	v_mfma_f32_16x16x32_bf16 v[180:183], v[90:93], v[220:223], v[0:3]
	s_mov_b32 m0, s43
	s_nop 4
	v_lshl_add_u64 v[0:1], v[240:241], 0, s[10:11]
	s_barrier
	ds_read_b128 v[208:211], v105 offset:49152
	ds_read_b128 v[212:215], v105 offset:50176
	ds_read_b128 v[216:219], v105 offset:51200
	ds_read_b128 v[220:223], v105 offset:52224
	ds_read_b128 v[224:227], v105 offset:53248
	ds_read_b128 v[228:231], v105 offset:54272
	ds_read_b128 v[232:235], v105 offset:55296
	ds_read_b128 v[236:239], v105 offset:56320
	global_load_lds_dwordx4 v[0:1], off
	v_lshl_add_u64 v[0:1], v[242:243], 0, s[10:11]
	s_mov_b32 m0, s60
	s_nop 0
	global_load_lds_dwordx4 v[0:1], off
	s_barrier
	s_waitcnt lgkmcnt(0)
	v_mfma_f32_16x16x32_bf16 v[0:3], v[184:187], v[208:211], v[4:7]
	v_mfma_f32_16x16x32_bf16 v[24:27], v[188:191], v[212:215], v[0:3]
	v_mfma_f32_16x16x32_bf16 v[0:3], v[192:195], v[208:211], v[156:159]
	v_mfma_f32_16x16x32_bf16 v[28:31], v[196:199], v[212:215], v[0:3]
	v_mfma_f32_16x16x32_bf16 v[0:3], v[184:187], v[216:219], v[160:163]
	v_mfma_f32_16x16x32_bf16 v[16:19], v[188:191], v[220:223], v[0:3]
	v_mfma_f32_16x16x32_bf16 v[0:3], v[192:195], v[216:219], v[164:167]
	v_mfma_f32_16x16x32_bf16 v[20:23], v[196:199], v[220:223], v[0:3]
	v_mfma_f32_16x16x32_bf16 v[0:3], v[184:187], v[224:227], v[168:171]
	v_mfma_f32_16x16x32_bf16 v[8:11], v[188:191], v[228:231], v[0:3]
	v_mfma_f32_16x16x32_bf16 v[0:3], v[192:195], v[224:227], v[172:175]
	v_mfma_f32_16x16x32_bf16 v[12:15], v[196:199], v[228:231], v[0:3]
	v_mfma_f32_16x16x32_bf16 v[0:3], v[184:187], v[232:235], v[132:135]
	v_mfma_f32_16x16x32_bf16 v[4:7], v[192:195], v[232:235], v[136:139]
	v_mfma_f32_16x16x32_bf16 v[0:3], v[188:191], v[236:239], v[0:3]
	v_mfma_f32_16x16x32_bf16 v[4:7], v[196:199], v[236:239], v[4:7]
	s_barrier
	s_add_u32 s24, s8, 0x18080
	s_addc_u32 s25, s9, 0
	s_mov_b32 m0, s81
	v_lshl_add_u64 v[132:133], s[24:25], 0, v[66:67]
	global_load_lds_dwordx4 v[132:133], off
	v_lshl_add_u64 v[132:133], s[24:25], 0, v[70:71]
	s_mov_b32 m0, s78
	s_nop 0
	global_load_lds_dwordx4 v[132:133], off
	s_waitcnt vmcnt(6)
	s_barrier
; __device__ __forceinline__ unsigned pk2(float lo, float hi) { unsigned r; asm("v_cvt_pk_bf16_f32 %0, %1, %2" : "=v"(r) : "v"(lo), "v"(hi)); return r; }
; __device__ __forceinline__ void unpack8(const u32x4 w, float (&f)[8]) { f[0] = bflo(w.x); f[1] = bfhi(w.x); f[2] = bflo(w.y); f[3] = bfhi(w.y); f[4] = bflo(w.z); f[5] = bfhi(w.z); f[6] = bflo(w.w); f[7] = bfhi(w.w); }
; __device__ __forceinline__ u32x4 pack8(const float (&f)[8]) { u32x4 o; o.x = pk2(f[0], f[1]); o.y = pk2(f[2], f[3]); o.z = pk2(f[4], f[5]); o.w = pk2(f[6], f[7]); return o; }
; __device__ __forceinline__ float sigmoidf_(float x) { return __builtin_amdgcn_rcpf(1.0f + __expf(-x)); }
;     __device__ __forceinline__ void operator()(const f32x4 (&acc)[2][2][4][2], const Unit& u, int wr, int wc, int fr, int fq) const {
;     ...
;         for (int ai = 0; ai < 2; ++ai)
; #pragma unroll
;             for (int m = 0; m < 4; ++m) { const f32x4 g0 = acc[ai][1][m][0], g1 = acc[ai][1][m][1]; u32x4 w; w.x = pk2(g0[0], g0[1]); w.y = pk2(g0[2], g0[3]); w.z = pk2(g1[0], g1[1]); w.w = pk2(g1[2], g1[3]);
;                 *(u32x4*)(G + (size_t)(row0 + ai * HALF + m * 16) * 512 + cb) = w; }
;         asm volatile("" ::: "memory");
; #pragma unroll
;         for (int ai = 0; ai < 2; ++ai)
; #pragma unroll
;             for (int m = 0; m < 4; ++m) { const int row = row0 + ai * HALF + m * 16; const size_t off = (size_t)row * 512 + cb; bf16_t* kp = RKV + (size_t)row * 1536 + 512 + cb;
;                 float ks[8], av[8], t[8]; unpack8(*(const u32x4*)kp, ks);
;                 { const f32x4 c0 = *(const f32x4*)(a0 + cb), c1 = *(const f32x4*)(a0 + cb + 4); const f32x4 x0 = acc[ai][0][m][0], x1 = acc[ai][0][m][1];
; #pragma unroll
;                   for (int j = 0; j < 4; ++j) { av[j] = sigmoidf_(c0[j] + x0[j]); av[4 + j] = sigmoidf_(c1[j] + x1[j]); } }
;                 { const f32x4 c0 = *(const f32x4*)(k_a + cb), c1 = *(const f32x4*)(k_a + cb + 4);
; #pragma unroll
;                   for (int j = 0; j < 4; ++j) { t[j] = ks[j] * (1.0f + (av[j] - 1.0f) * c0[j]); t[4 + j] = ks[4 + j] * (1.0f + (av[4 + j] - 1.0f) * c1[j]); } }
;                 *(u32x4*)kp = pack8(t);
;                 { const f32x4 c0 = *(const f32x4*)(k_k + cb), c1 = *(const f32x4*)(k_k + cb + 4); const float ri = rinv[row * 8 + (cb >> 6)];
	v_mfma_f32_16x16x32_bf16 v[132:135], v[78:81], v[208:211], v[140:143]
	v_mfma_f32_16x16x32_bf16 v[112:115], v[78:81], v[216:219], v[112:115]
	v_mfma_f32_16x16x32_bf16 v[124:127], v[78:81], v[224:227], v[124:127]
	v_mfma_f32_16x16x32_bf16 v[78:81], v[78:81], v[232:235], v[98:101]
	v_mfma_f32_16x16x32_bf16 v[136:139], v[86:89], v[208:211], v[144:147]
	v_mfma_f32_16x16x32_bf16 v[116:119], v[86:89], v[216:219], v[116:119]
	v_mfma_f32_16x16x32_bf16 v[128:131], v[86:89], v[224:227], v[128:131]
	v_mfma_f32_16x16x32_bf16 v[140:143], v[82:85], v[236:239], v[78:81]
	v_mfma_f32_16x16x32_bf16 v[78:81], v[86:89], v[232:235], v[108:111]
	v_mfma_f32_16x16x32_bf16 v[132:135], v[82:85], v[212:215], v[132:135]
	v_mfma_f32_16x16x32_bf16 v[136:139], v[90:93], v[212:215], v[136:139]
	v_mfma_f32_16x16x32_bf16 v[112:115], v[82:85], v[220:223], v[112:115]
	v_mfma_f32_16x16x32_bf16 v[116:119], v[90:93], v[220:223], v[116:119]
	v_mfma_f32_16x16x32_bf16 v[124:127], v[82:85], v[228:231], v[124:127]
	v_mfma_f32_16x16x32_bf16 v[128:131], v[90:93], v[228:231], v[128:131]
	v_mfma_f32_16x16x32_bf16 v[84:87], v[90:93], v[236:239], v[78:81]
	s_lshl_b32 s24, s71, 7
	v_lshl_add_u32 v100, s70, 8, v102
	s_or_b32 s24, s24, s42
	v_or_b32_e32 v78, s24, v103
	v_ashrrev_i32_e32 v101, 31, v100
	v_ashrrev_i32_e32 v79, 31, v78
	v_lshlrev_b64 v[80:81], 10, v[100:101]
	v_lshl_add_u64 v[80:81], s[52:53], 0, v[80:81]
	v_lshlrev_b64 v[82:83], 1, v[78:79]
	v_or_b32_e32 v98, 16, v100
	v_lshl_add_u64 v[80:81], v[80:81], 0, v[82:83]
	v_ashrrev_i32_e32 v99, 31, v98
	s_barrier
	v_cvt_pk_bf16_f32 v88, v94, v95
	v_cvt_pk_bf16_f32 v89, v96, v97
	v_cvt_pk_bf16_f32 v90, v200, v201
	v_cvt_pk_bf16_f32 v91, v202, v203
	global_store_dwordx4 v[80:81], v[88:91], off nt
	v_lshlrev_b64 v[80:81], 10, v[98:99]
	v_lshl_add_u64 v[80:81], s[52:53], 0, v[80:81]
	v_or_b32_e32 v96, 32, v100
	v_lshl_add_u64 v[80:81], v[80:81], 0, v[82:83]
	v_ashrrev_i32_e32 v97, 31, v96
	v_cvt_pk_bf16_f32 v88, v120, v121
	v_cvt_pk_bf16_f32 v89, v122, v123
	v_cvt_pk_bf16_f32 v90, v204, v205
	v_cvt_pk_bf16_f32 v91, v206, v207
	global_store_dwordx4 v[80:81], v[88:91], off nt
	v_lshlrev_b64 v[80:81], 10, v[96:97]
	v_lshl_add_u64 v[80:81], s[52:53], 0, v[80:81]
	v_or_b32_e32 v94, 48, v100
	v_lshl_add_u64 v[80:81], v[80:81], 0, v[82:83]
	v_ashrrev_i32_e32 v95, 31, v94
	v_cvt_pk_bf16_f32 v88, v148, v149
	v_cvt_pk_bf16_f32 v89, v150, v151
	v_cvt_pk_bf16_f32 v90, v152, v153
	v_cvt_pk_bf16_f32 v91, v154, v155
	global_store_dwordx4 v[80:81], v[88:91], off nt
	v_lshlrev_b64 v[80:81], 10, v[94:95]
	v_lshl_add_u64 v[80:81], s[52:53], 0, v[80:81]
	v_add_u32_e32 v92, 0x80, v100
	v_lshl_add_u64 v[80:81], v[80:81], 0, v[82:83]
	v_ashrrev_i32_e32 v93, 31, v92
	v_cvt_pk_bf16_f32 v88, v176, v177
	v_cvt_pk_bf16_f32 v89, v178, v179
	v_cvt_pk_bf16_f32 v90, v180, v181
	v_cvt_pk_bf16_f32 v91, v182, v183
	global_store_dwordx4 v[80:81], v[88:91], off nt
	v_lshlrev_b64 v[80:81], 10, v[92:93]
	v_lshl_add_u64 v[80:81], s[52:53], 0, v[80:81]
	v_cvt_pk_bf16_f32 v90, v136, v137
	v_lshl_add_u64 v[80:81], v[80:81], 0, v[82:83]
	v_cvt_pk_bf16_f32 v88, v132, v133
	v_cvt_pk_bf16_f32 v89, v134, v135
	v_cvt_pk_bf16_f32 v91, v138, v139
	global_store_dwordx4 v[80:81], v[88:91], off nt
	v_cvt_pk_bf16_f32 v108, v112, v113
	v_cvt_pk_bf16_f32 v109, v114, v115
	v_cvt_pk_bf16_f32 v110, v116, v117
	v_cvt_pk_bf16_f32 v111, v118, v119
	s_ashr_i32 s24, s24, 6
	s_nop 0
	v_add_u32_e32 v90, 0x90, v100
	v_ashrrev_i32_e32 v91, 31, v90
	v_lshlrev_b64 v[80:81], 10, v[90:91]
	v_lshl_add_u64 v[80:81], s[52:53], 0, v[80:81]
	v_add_u32_e32 v88, 0xa0, v100
	v_lshl_add_u64 v[80:81], v[80:81], 0, v[82:83]
	v_ashrrev_i32_e32 v89, 31, v88
	global_store_dwordx4 v[80:81], v[108:111], off nt
	v_lshlrev_b64 v[80:81], 10, v[88:89]
	v_lshl_add_u64 v[80:81], s[52:53], 0, v[80:81]
	v_lshl_add_u64 v[80:81], v[80:81], 0, v[82:83]
	v_cvt_pk_bf16_f32 v108, v124, v125
	v_cvt_pk_bf16_f32 v109, v126, v127
	v_cvt_pk_bf16_f32 v110, v128, v129
	v_cvt_pk_bf16_f32 v111, v130, v131
	global_store_dwordx4 v[80:81], v[108:111], off nt
	v_add_u32_e32 v80, 0xb0, v100
	v_ashrrev_i32_e32 v81, 31, v80
	v_cvt_pk_bf16_f32 v110, v84, v85
	v_lshlrev_b64 v[84:85], 10, v[80:81]
	v_lshl_add_u64 v[84:85], s[52:53], 0, v[84:85]
	v_lshl_add_u64 v[84:85], v[84:85], 0, v[82:83]
	v_cvt_pk_bf16_f32 v108, v140, v141
	v_cvt_pk_bf16_f32 v109, v142, v143
	v_cvt_pk_bf16_f32 v111, v86, v87
	global_store_dwordx4 v[84:85], v[108:111], off nt
	v_mad_i64_i32 v[84:85], s[26:27], v100, s68, v[76:77]
	v_lshlrev_b64 v[130:131], 2, v[78:79]
	v_lshl_add_u64 v[128:129], v[84:85], 0, v[82:83]
	v_lshl_add_u64 v[84:85], s[22:23], 0, v[130:131]
	global_load_dwordx4 v[108:111], v[128:129], off offset:1024
	global_load_dwordx4 v[112:115], v[84:85], off
	global_load_dwordx4 v[116:119], v[84:85], off offset:16
	v_lshl_add_u64 v[86:87], s[30:31], 0, v[130:131]
	global_load_dwordx4 v[120:123], v[86:87], off
	global_load_dwordx4 v[124:127], v[86:87], off offset:16
	global_load_dwordx4 v[156:159], v130, s[22:23]
	global_load_dwordx4 v[160:163], v130, s[22:23] offset:16
	global_load_dwordx4 v[164:167], v130, s[30:31]
	global_load_dwordx4 v[168:171], v130, s[30:31] offset:16
	global_load_dwordx4 v[184:187], v130, s[28:29]
	global_load_dwordx4 v[188:191], v130, s[28:29] offset:16
	v_lshl_add_u32 v238, v100, 3, s24
	v_lshlrev_b32_e32 v238, 2, v238
	v_add_u32_e32 v239, 0x1000, v238
	global_load_dword v228, v238, s[4:5]
	global_load_dword v229, v238, s[4:5] offset:512
	global_load_dword v230, v238, s[4:5] offset:1024
	global_load_dword v231, v238, s[4:5] offset:1536
	global_load_dword v232, v239, s[4:5]
	global_load_dword v233, v239, s[4:5] offset:512
	global_load_dword v234, v239, s[4:5] offset:1024
	global_load_dword v235, v239, s[4:5] offset:1536
	s_mov_b32 s98, 0xc000
	s_mov_b32 s99, 0
	v_lshl_add_u64 v[236:237], v[128:129], 0, s[98:99]
	global_load_dwordx4 v[192:195], v[236:237], off offset:1024
	s_mov_b32 s98, 0x18000
	s_mov_b32 s99, 0
	v_lshl_add_u64 v[236:237], v[128:129], 0, s[98:99]
	global_load_dwordx4 v[196:199], v[236:237], off offset:1024
	s_mov_b32 s98, 0x24000
	s_mov_b32 s99, 0
	v_lshl_add_u64 v[236:237], v[128:129], 0, s[98:99]
	global_load_dwordx4 v[208:211], v[236:237], off offset:1024
	s_mov_b32 s98, 0x60000
	s_mov_b32 s99, 0
	v_lshl_add_u64 v[236:237], v[128:129], 0, s[98:99]
	global_load_dwordx4 v[212:215], v[236:237], off offset:1024
	s_mov_b32 s98, 0x6c000
	s_mov_b32 s99, 0
	v_lshl_add_u64 v[236:237], v[128:129], 0, s[98:99]
	global_load_dwordx4 v[216:219], v[236:237], off offset:1024
	s_mov_b32 s98, 0x78000
	s_mov_b32 s99, 0
	v_lshl_add_u64 v[236:237], v[128:129], 0, s[98:99]
	global_load_dwordx4 v[220:223], v[236:237], off offset:1024
	s_mov_b32 s98, 0x84000
	s_mov_b32 s99, 0
	v_lshl_add_u64 v[236:237], v[128:129], 0, s[98:99]
	global_load_dwordx4 v[224:227], v[236:237], off offset:1024
	s_add_i32 s65, s65, s96
	s_andn2_b64 vcc, exec, s[6:7]
	s_mov_b32 s71, s3
	s_mov_b32 s70, s69
	s_waitcnt vmcnt(0)
; __device__ __forceinline__ void unpack8(const u32x4 w, float (&f)[8]) { f[0] = bflo(w.x); f[1] = bfhi(w.x); f[2] = bflo(w.y); f[3] = bfhi(w.y); f[4] = bflo(w.z); f[5] = bfhi(w.z); f[6] = bflo(w.w); f[7] = bfhi(w.w); }
; __device__ __forceinline__ u32x4 pack8(const float (&f)[8]) { u32x4 o; o.x = pk2(f[0], f[1]); o.y = pk2(f[2], f[3]); o.z = pk2(f[4], f[5]); o.w = pk2(f[6], f[7]); return o; }
; __device__ __forceinline__ float sigmoidf_(float x) { return __builtin_amdgcn_rcpf(1.0f + __expf(-x)); }
;     __device__ __forceinline__ void operator()(const f32x4 (&acc)[2][2][4][2], const Unit& u, int wr, int wc, int fr, int fq) const {
;     ...
;             for (int m = 0; m < 4; ++m) { const int row = row0 + ai * HALF + m * 16; const size_t off = (size_t)row * 512 + cb; bf16_t* kp = RKV + (size_t)row * 1536 + 512 + cb;
;                 float ks[8], av[8], t[8]; unpack8(*(const u32x4*)kp, ks);
;                 { const f32x4 c0 = *(const f32x4*)(a0 + cb), c1 = *(const f32x4*)(a0 + cb + 4); const f32x4 x0 = acc[ai][0][m][0], x1 = acc[ai][0][m][1];
; #pragma unroll
;                   for (int j = 0; j < 4; ++j) { av[j] = sigmoidf_(c0[j] + x0[j]); av[4 + j] = sigmoidf_(c1[j] + x1[j]); } }
;                 { const f32x4 c0 = *(const f32x4*)(k_a + cb), c1 = *(const f32x4*)(k_a + cb + 4);
; #pragma unroll
;                   for (int j = 0; j < 4; ++j) { t[j] = ks[j] * (1.0f + (av[j] - 1.0f) * c0[j]); t[4 + j] = ks[4 + j] * (1.0f + (av[4 + j] - 1.0f) * c1[j]); } }
;                 *(u32x4*)kp = pack8(t);
;                 { const f32x4 c0 = *(const f32x4*)(k_k + cb), c1 = *(const f32x4*)(k_k + cb + 4); const float ri = rinv[row * 8 + (cb >> 6)];
; #pragma unroll
;                   for (int j = 0; j < 4; ++j) { t[j] = ks[j] * c0[j] * ri; t[4 + j] = ks[4 + j] * c1[j] * ri; } }
;                 *(u32x4*)(KK + off) = pack8(t);
; #pragma unroll
;                 for (int e = 0; e < 8; ++e) t[e] = -t[e] * av[e];
;                 *(u32x4*)(NB + off) = pack8(t);
;                 asm volatile("" ::: "memory"); }
	v_add_f32_e32 v60, v60, v112
	v_mul_f32_e32 v60, 0xbfb8aa3b, v60
	v_exp_f32_e32 v60, v60
	v_add_f32_e32 v56, v56, v116
	v_mul_f32_e32 v56, 0xbfb8aa3b, v56
	v_exp_f32_e32 v56, v56
	v_add_f32_e32 v60, 1.0, v60
	v_rcp_f32_e32 v116, v60
	v_add_f32_e32 v60, v61, v113
	v_mul_f32_e32 v60, 0xbfb8aa3b, v60
	v_add_f32_e32 v57, v57, v117
	v_exp_f32_e32 v60, v60
	v_mul_f32_e32 v57, 0xbfb8aa3b, v57
	v_exp_f32_e32 v57, v57
	v_add_f32_e32 v56, 1.0, v56
	v_rcp_f32_e32 v113, v56
	v_add_f32_e32 v56, 1.0, v60
	v_rcp_f32_e32 v117, v56
	v_add_f32_e32 v56, 1.0, v57
	v_add_f32_e32 v57, v62, v114
	v_mul_f32_e32 v57, 0xbfb8aa3b, v57
	v_add_f32_e32 v58, v58, v118
	v_exp_f32_e32 v57, v57
	v_mul_f32_e32 v58, 0xbfb8aa3b, v58
	v_exp_f32_e32 v58, v58
	v_rcp_f32_e32 v114, v56
	v_add_f32_e32 v56, 1.0, v57
	v_add_f32_e32 v57, v63, v115
	v_rcp_f32_e32 v118, v56
	v_add_f32_e32 v56, 1.0, v58
	v_mul_f32_e32 v57, 0xbfb8aa3b, v57
	v_add_f32_e32 v58, v59, v119
	v_exp_f32_e32 v57, v57
	v_mul_f32_e32 v58, 0xbfb8aa3b, v58
	v_exp_f32_e32 v58, v58
	v_rcp_f32_e32 v115, v56
	v_add_f32_e32 v56, 1.0, v57
	v_rcp_f32_e32 v119, v56
	v_add_f32_e32 v56, 1.0, v58
	v_rcp_f32_e32 v139, v56
	v_add_f32_e32 v57, -1.0, v113
	v_lshlrev_b32_e32 v136, 16, v110
	v_fma_f32 v57, v124, v57, 1.0
	v_add_f32_e32 v56, -1.0, v116
	v_mul_f32_e32 v58, v57, v136
	v_add_f32_e32 v57, -1.0, v117
	v_add_f32_e32 v62, -1.0, v119
	v_lshlrev_b32_e32 v132, 16, v108
	v_and_b32_e32 v133, 0xffff0000, v108
	v_and_b32_e32 v135, 0xffff0000, v109
	v_fma_f32 v56, v120, v56, 1.0
	v_fma_f32 v57, v121, v57, 1.0
	v_add_f32_e32 v59, -1.0, v114
	v_add_f32_e32 v60, -1.0, v118
	v_fma_f32 v62, v123, v62, 1.0
	v_add_f32_e32 v63, -1.0, v139
	v_lshlrev_b32_e32 v134, 16, v109
	v_and_b32_e32 v137, 0xffff0000, v110
	v_and_b32_e32 v112, 0xffff0000, v111
	v_mul_f32_e32 v56, v56, v132
	v_mul_f32_e32 v57, v57, v133
	v_fma_f32 v59, v125, v59, 1.0
	v_fma_f32 v60, v122, v60, 1.0
	v_add_f32_e32 v61, -1.0, v115
	v_mul_f32_e32 v62, v62, v135
	v_fma_f32 v63, v127, v63, 1.0
	v_lshlrev_b32_e32 v138, 16, v111
	v_mul_f32_e32 v59, v59, v137
	v_mul_f32_e32 v60, v60, v134
	v_fma_f32 v61, v126, v61, 1.0
	v_mul_f32_e32 v63, v63, v112
	v_cvt_pk_bf16_f32 v56, v56, v57
	v_cvt_pk_bf16_f32 v57, v60, v62
	v_lshl_add_u32 v62, v100, 3, s24
	v_mul_f32_e32 v61, v61, v138
	v_cvt_pk_bf16_f32 v58, v58, v59
	v_cvt_pk_bf16_f32 v59, v61, v63
	global_store_dwordx4 v[128:129], v[56:59], off offset:1024
	v_ashrrev_i32_e32 v63, 31, v62
	v_lshl_add_u64 v[62:63], v[62:63], 2, s[4:5]
	v_lshl_add_u64 v[56:57], s[28:29], 0, v[130:131]
	s_nop 1
	v_mov_b32_e32 v58, v184
	v_mov_b32_e32 v59, v185
	v_mov_b32_e32 v60, v186
	v_mov_b32_e32 v61, v187
	s_nop 1
	v_mov_b32_e32 v120, v228
	s_nop 1
	v_mov_b32_e32 v108, v188
	v_mov_b32_e32 v109, v189
	v_mov_b32_e32 v110, v190
	v_mov_b32_e32 v111, v191
	v_lshlrev_b64 v[62:63], 9, v[100:101]
	v_lshl_add_u64 v[62:63], v[62:63], 0, v[78:79]
	v_lshlrev_b64 v[62:63], 1, v[62:63]
	v_lshl_add_u64 v[100:101], s[50:51], 0, v[62:63]
	v_lshl_add_u64 v[62:63], s[62:63], 0, v[62:63]
	v_mul_f32_e32 v58, v58, v132
	v_mul_f32_e32 v121, v58, v120
	v_mul_f32_e32 v58, v108, v136
	v_mul_f32_e32 v108, v120, v58
	v_mul_f32_e32 v58, v59, v133
	v_mul_f32_e32 v122, v58, v120
	v_mul_f32_e32 v58, v109, v137
	v_mul_f32_e32 v109, v120, v58
	v_mul_f32_e32 v58, v60, v134
	v_mul_f32_e32 v123, v58, v120
	v_mul_f32_e32 v58, v110, v138
	v_mul_f32_e32 v110, v120, v58
	v_mul_f32_e32 v58, v61, v135
	v_mul_f32_e32 v124, v58, v120
	v_mul_f32_e32 v58, v111, v112
	v_mul_f32_e32 v111, v120, v58
	v_cvt_pk_bf16_f32 v58, v121, v122
	v_cvt_pk_bf16_f32 v59, v123, v124
	v_cvt_pk_bf16_f32 v60, v108, v109
	v_cvt_pk_bf16_f32 v61, v110, v111
	global_store_dwordx4 v[100:101], v[58:61], off
	v_mul_f32_e64 v100, v113, -v108
	v_mul_f32_e64 v101, v114, -v109
	v_mul_f32_e64 v58, v116, -v121
	v_mul_f32_e64 v59, v117, -v122
	v_mul_f32_e64 v60, v118, -v123
	v_mul_f32_e64 v61, v119, -v124
	v_cvt_pk_bf16_f32 v58, v58, v59
	v_cvt_pk_bf16_f32 v59, v60, v61
	v_mul_f32_e64 v108, v115, -v110
	v_mul_f32_e64 v109, v139, -v111
	v_cvt_pk_bf16_f32 v60, v100, v101
	v_cvt_pk_bf16_f32 v61, v108, v109
	global_store_dwordx4 v[62:63], v[58:61], off
	s_nop 1
	v_mad_i64_i32 v[58:59], s[26:27], v98, s68, v[76:77]
	v_lshl_add_u64 v[62:63], v[58:59], 0, v[82:83]
	s_nop 1
	v_mov_b32_e32 v58, v192
	v_mov_b32_e32 v59, v193
	v_mov_b32_e32 v60, v194
	v_mov_b32_e32 v61, v195
	s_nop 1
	v_mov_b32_e32 v108, v156
	v_mov_b32_e32 v109, v157
	v_mov_b32_e32 v110, v158
	v_mov_b32_e32 v111, v159
	s_nop 1
	v_mov_b32_e32 v112, v160
	v_mov_b32_e32 v113, v161
	v_mov_b32_e32 v114, v162
	v_mov_b32_e32 v115, v163
	s_nop 1
	v_mov_b32_e32 v116, v164
	v_mov_b32_e32 v117, v165
	v_mov_b32_e32 v118, v166
	v_mov_b32_e32 v119, v167
	s_nop 1
	v_mov_b32_e32 v120, v168
	v_mov_b32_e32 v121, v169
	v_mov_b32_e32 v122, v170
	v_mov_b32_e32 v123, v171
	v_lshlrev_b32_e32 v126, 16, v60
	v_add_f32_e32 v48, v48, v108
	v_add_f32_e32 v52, v52, v112
	v_mul_f32_e32 v52, 0xbfb8aa3b, v52
	v_add_f32_e32 v49, v49, v109
	v_add_f32_e32 v53, v53, v113
	v_exp_f32_e32 v52, v52
	v_add_f32_e32 v50, v50, v110
	v_add_f32_e32 v54, v54, v114
	v_add_f32_e32 v51, v51, v111
	v_add_f32_e32 v55, v55, v115
	v_mul_f32_e32 v48, 0xbfb8aa3b, v48
	v_mul_f32_e32 v49, 0xbfb8aa3b, v49
	v_mul_f32_e32 v53, 0xbfb8aa3b, v53
	v_mul_f32_e32 v50, 0xbfb8aa3b, v50
	v_mul_f32_e32 v54, 0xbfb8aa3b, v54
	v_mul_f32_e32 v51, 0xbfb8aa3b, v51
	v_mul_f32_e32 v55, 0xbfb8aa3b, v55
	v_exp_f32_e32 v48, v48
	v_exp_f32_e32 v49, v49
	v_exp_f32_e32 v53, v53
	v_exp_f32_e32 v50, v50
	v_exp_f32_e32 v54, v54
	v_exp_f32_e32 v51, v51
	v_exp_f32_e32 v55, v55
	v_add_f32_e32 v52, 1.0, v52
	v_rcp_f32_e32 v109, v52
	v_add_f32_e32 v48, 1.0, v48
; __device__ __forceinline__ void unpack8(const u32x4 w, float (&f)[8]) { f[0] = bflo(w.x); f[1] = bfhi(w.x); f[2] = bflo(w.y); f[3] = bfhi(w.y); f[4] = bflo(w.z); f[5] = bfhi(w.z); f[6] = bflo(w.w); f[7] = bfhi(w.w); }
; __device__ __forceinline__ u32x4 pack8(const float (&f)[8]) { u32x4 o; o.x = pk2(f[0], f[1]); o.y = pk2(f[2], f[3]); o.z = pk2(f[4], f[5]); o.w = pk2(f[6], f[7]); return o; }
; __device__ __forceinline__ float sigmoidf_(float x) { return __builtin_amdgcn_rcpf(1.0f + __expf(-x)); }
;     __device__ __forceinline__ void operator()(const f32x4 (&acc)[2][2][4][2], const Unit& u, int wr, int wc, int fr, int fq) const {
;     ...
;             for (int m = 0; m < 4; ++m) { const int row = row0 + ai * HALF + m * 16; const size_t off = (size_t)row * 512 + cb; bf16_t* kp = RKV + (size_t)row * 1536 + 512 + cb;
;                 float ks[8], av[8], t[8]; unpack8(*(const u32x4*)kp, ks);
;                 { const f32x4 c0 = *(const f32x4*)(a0 + cb), c1 = *(const f32x4*)(a0 + cb + 4); const f32x4 x0 = acc[ai][0][m][0], x1 = acc[ai][0][m][1];
; #pragma unroll
;                   for (int j = 0; j < 4; ++j) { av[j] = sigmoidf_(c0[j] + x0[j]); av[4 + j] = sigmoidf_(c1[j] + x1[j]); } }
;                 { const f32x4 c0 = *(const f32x4*)(k_a + cb), c1 = *(const f32x4*)(k_a + cb + 4);
; #pragma unroll
;                   for (int j = 0; j < 4; ++j) { t[j] = ks[j] * (1.0f + (av[j] - 1.0f) * c0[j]); t[4 + j] = ks[4 + j] * (1.0f + (av[4 + j] - 1.0f) * c1[j]); } }
;                 *(u32x4*)kp = pack8(t);
;                 { const f32x4 c0 = *(const f32x4*)(k_k + cb), c1 = *(const f32x4*)(k_k + cb + 4); const float ri = rinv[row * 8 + (cb >> 6)];
; #pragma unroll
;                   for (int j = 0; j < 4; ++j) { t[j] = ks[j] * c0[j] * ri; t[4 + j] = ks[4 + j] * c1[j] * ri; } }
;                 *(u32x4*)(KK + off) = pack8(t);
; #pragma unroll
;                 for (int e = 0; e < 8; ++e) t[e] = -t[e] * av[e];
;                 *(u32x4*)(NB + off) = pack8(t);
;                 asm volatile("" ::: "memory"); }
	v_add_f32_e32 v49, 1.0, v49
	v_add_f32_e32 v53, 1.0, v53
	v_add_f32_e32 v50, 1.0, v50
	v_add_f32_e32 v54, 1.0, v54
	v_add_f32_e32 v51, 1.0, v51
	v_add_f32_e32 v55, 1.0, v55
	v_rcp_f32_e32 v108, v48
	v_rcp_f32_e32 v110, v49
	v_rcp_f32_e32 v111, v53
	v_rcp_f32_e32 v112, v50
	v_rcp_f32_e32 v113, v54
	v_rcp_f32_e32 v114, v51
	v_rcp_f32_e32 v115, v55
	v_add_f32_e32 v49, -1.0, v109
	v_fma_f32 v49, v120, v49, 1.0
	v_add_f32_e32 v48, -1.0, v108
	v_mul_f32_e32 v50, v49, v126
	v_add_f32_e32 v49, -1.0, v110
	v_add_f32_e32 v51, -1.0, v111
	v_lshlrev_b32_e32 v100, 16, v58
	v_and_b32_e32 v101, 0xffff0000, v58
	v_and_b32_e32 v127, 0xffff0000, v60
	v_fma_f32 v48, v116, v48, 1.0
	v_fma_f32 v49, v117, v49, 1.0
	v_fma_f32 v51, v121, v51, 1.0
	v_add_f32_e32 v52, -1.0, v112
	v_add_f32_e32 v53, -1.0, v113
	v_add_f32_e32 v54, -1.0, v114
	v_add_f32_e32 v55, -1.0, v115
	v_lshlrev_b32_e32 v124, 16, v59
	v_and_b32_e32 v125, 0xffff0000, v59
	v_lshlrev_b32_e32 v128, 16, v61
	v_and_b32_e32 v129, 0xffff0000, v61
	v_mul_f32_e32 v48, v48, v100
	v_mul_f32_e32 v49, v49, v101
	v_mul_f32_e32 v51, v51, v127
	v_fma_f32 v52, v118, v52, 1.0
	v_fma_f32 v53, v122, v53, 1.0
	v_fma_f32 v54, v119, v54, 1.0
	v_fma_f32 v55, v123, v55, 1.0
	v_lshl_add_u32 v58, v98, 3, s24
	v_mul_f32_e32 v52, v52, v124
	v_mul_f32_e32 v53, v53, v128
	v_mul_f32_e32 v54, v54, v125
	v_mul_f32_e32 v55, v55, v129
	v_cvt_pk_bf16_f32 v48, v48, v49
	v_cvt_pk_bf16_f32 v49, v52, v54
	v_cvt_pk_bf16_f32 v50, v50, v51
	v_cvt_pk_bf16_f32 v51, v53, v55
	global_store_dwordx4 v[62:63], v[48:51], off offset:1024
	v_ashrrev_i32_e32 v59, 31, v58
	s_nop 1
	v_mov_b32_e32 v48, v184
	v_mov_b32_e32 v49, v185
	v_mov_b32_e32 v50, v186
	v_mov_b32_e32 v51, v187
	s_nop 1
	v_mov_b32_e32 v52, v188
	v_mov_b32_e32 v53, v189
	v_mov_b32_e32 v54, v190
	v_mov_b32_e32 v55, v191
	v_lshl_add_u64 v[58:59], v[58:59], 2, s[4:5]
	s_nop 1
	v_mov_b32_e32 v116, v229
	v_lshlrev_b64 v[60:61], 9, v[98:99]
	v_lshl_add_u64 v[60:61], v[60:61], 0, v[78:79]
	v_mad_i64_i32 v[58:59], s[26:27], v96, s68, v[76:77]
	v_lshlrev_b64 v[60:61], 1, v[60:61]
	v_lshl_add_u64 v[62:63], v[58:59], 0, v[82:83]
	v_lshl_add_u64 v[58:59], s[50:51], 0, v[60:61]
	v_lshl_add_u64 v[60:61], s[62:63], 0, v[60:61]
	v_mul_f32_e32 v48, v48, v100
	v_mul_f32_e32 v52, v52, v126
	v_mul_f32_e32 v49, v49, v101
	v_mul_f32_e32 v53, v53, v127
	v_mul_f32_e32 v50, v50, v124
	v_mul_f32_e32 v54, v54, v128
	v_mul_f32_e32 v51, v51, v125
	v_mul_f32_e32 v55, v55, v129
	v_mul_f32_e32 v98, v48, v116
	v_mul_f32_e32 v52, v116, v52
	v_mul_f32_e32 v99, v49, v116
	v_mul_f32_e32 v53, v116, v53
	v_mul_f32_e32 v100, v50, v116
	v_mul_f32_e32 v54, v116, v54
	v_mul_f32_e32 v101, v51, v116
	v_mul_f32_e32 v55, v116, v55
	v_cvt_pk_bf16_f32 v48, v98, v99
	v_cvt_pk_bf16_f32 v49, v100, v101
	v_cvt_pk_bf16_f32 v50, v52, v53
	v_cvt_pk_bf16_f32 v51, v54, v55
	v_mul_f32_e64 v98, v108, -v98
	v_mul_f32_e64 v99, v110, -v99
	v_mul_f32_e64 v100, v112, -v100
	v_mul_f32_e64 v101, v114, -v101
	v_mul_f32_e64 v52, v109, -v52
	v_mul_f32_e64 v53, v111, -v53
	v_mul_f32_e64 v54, v113, -v54
	v_mul_f32_e64 v55, v115, -v55
	global_store_dwordx4 v[58:59], v[48:51], off
	s_nop 1
	v_cvt_pk_bf16_f32 v48, v98, v99
	v_cvt_pk_bf16_f32 v49, v100, v101
	v_cvt_pk_bf16_f32 v50, v52, v53
	v_cvt_pk_bf16_f32 v51, v54, v55
	global_store_dwordx4 v[60:61], v[48:51], off
	s_nop 1
	v_mov_b32_e32 v48, v196
	v_mov_b32_e32 v49, v197
	v_mov_b32_e32 v50, v198
	v_mov_b32_e32 v51, v199
	s_nop 1
	v_mov_b32_e32 v52, v156
	v_mov_b32_e32 v53, v157
	v_mov_b32_e32 v54, v158
	v_mov_b32_e32 v55, v159
	s_nop 1
	v_mov_b32_e32 v58, v160
	v_mov_b32_e32 v59, v161
	v_mov_b32_e32 v60, v162
	v_mov_b32_e32 v61, v163
	s_nop 1
	v_mov_b32_e32 v98, v164
	v_mov_b32_e32 v99, v165
	v_mov_b32_e32 v100, v166
	v_mov_b32_e32 v101, v167
	s_nop 1
	v_mov_b32_e32 v108, v168
	v_mov_b32_e32 v109, v169
	v_mov_b32_e32 v110, v170
	v_mov_b32_e32 v111, v171
	v_and_b32_e32 v113, 0xffff0000, v48
	v_add_f32_e32 v41, v41, v53
	v_add_f32_e32 v44, v44, v58
	v_add_f32_e32 v45, v45, v59
	v_add_f32_e32 v40, v40, v52
	v_add_f32_e32 v42, v42, v54
	v_mul_f32_e32 v44, 0xbfb8aa3b, v44
	v_mul_f32_e32 v41, 0xbfb8aa3b, v41
	v_mul_f32_e32 v45, 0xbfb8aa3b, v45
	v_add_f32_e32 v46, v46, v60
	v_add_f32_e32 v43, v43, v55
	v_add_f32_e32 v47, v47, v61
	v_mul_f32_e32 v40, 0xbfb8aa3b, v40
	v_mul_f32_e32 v42, 0xbfb8aa3b, v42
	v_exp_f32_e32 v44, v44
	v_exp_f32_e32 v41, v41
	v_exp_f32_e32 v45, v45
	v_mul_f32_e32 v46, 0xbfb8aa3b, v46
	v_mul_f32_e32 v43, 0xbfb8aa3b, v43
	v_mul_f32_e32 v47, 0xbfb8aa3b, v47
	v_exp_f32_e32 v40, v40
	v_exp_f32_e32 v42, v42
	v_exp_f32_e32 v46, v46
	v_exp_f32_e32 v43, v43
	v_exp_f32_e32 v47, v47
	v_add_f32_e32 v44, 1.0, v44
	v_add_f32_e32 v41, 1.0, v41
	v_add_f32_e32 v45, 1.0, v45
	v_add_f32_e32 v40, 1.0, v40
	v_add_f32_e32 v42, 1.0, v42
	v_rcp_f32_e32 v53, v44
	v_rcp_f32_e32 v54, v41
	v_rcp_f32_e32 v55, v45
	v_add_f32_e32 v46, 1.0, v46
	v_add_f32_e32 v43, 1.0, v43
	v_add_f32_e32 v47, 1.0, v47
	v_rcp_f32_e32 v52, v40
	v_rcp_f32_e32 v58, v42
	v_rcp_f32_e32 v59, v46
	v_rcp_f32_e32 v60, v43
	v_rcp_f32_e32 v61, v47
	v_add_f32_e32 v41, -1.0, v53
	v_add_f32_e32 v42, -1.0, v54
	v_add_f32_e32 v43, -1.0, v55
	v_lshlrev_b32_e32 v116, 16, v50
	v_and_b32_e32 v117, 0xffff0000, v50
	v_add_f32_e32 v40, -1.0, v52
	v_add_f32_e32 v44, -1.0, v58
	v_fma_f32 v41, v108, v41, 1.0
	v_fma_f32 v42, v99, v42, 1.0
	v_fma_f32 v43, v109, v43, 1.0
	v_lshlrev_b32_e32 v112, 16, v48
	v_lshlrev_b32_e32 v114, 16, v49
	v_add_f32_e32 v45, -1.0, v59
	v_add_f32_e32 v46, -1.0, v60
	v_add_f32_e32 v47, -1.0, v61
	v_fma_f32 v40, v98, v40, 1.0
	v_fma_f32 v44, v100, v44, 1.0
	v_mul_f32_e32 v48, v41, v116
	v_mul_f32_e32 v41, v42, v113
	v_mul_f32_e32 v42, v43, v117
; __device__ __forceinline__ void unpack8(const u32x4 w, float (&f)[8]) { f[0] = bflo(w.x); f[1] = bfhi(w.x); f[2] = bflo(w.y); f[3] = bfhi(w.y); f[4] = bflo(w.z); f[5] = bfhi(w.z); f[6] = bflo(w.w); f[7] = bfhi(w.w); }
; __device__ __forceinline__ u32x4 pack8(const float (&f)[8]) { u32x4 o; o.x = pk2(f[0], f[1]); o.y = pk2(f[2], f[3]); o.z = pk2(f[4], f[5]); o.w = pk2(f[6], f[7]); return o; }
; __device__ __forceinline__ float sigmoidf_(float x) { return __builtin_amdgcn_rcpf(1.0f + __expf(-x)); }
;     __device__ __forceinline__ void operator()(const f32x4 (&acc)[2][2][4][2], const Unit& u, int wr, int wc, int fr, int fq) const {
;     ...
;             for (int m = 0; m < 4; ++m) { const int row = row0 + ai * HALF + m * 16; const size_t off = (size_t)row * 512 + cb; bf16_t* kp = RKV + (size_t)row * 1536 + 512 + cb;
;                 float ks[8], av[8], t[8]; unpack8(*(const u32x4*)kp, ks);
;                 { const f32x4 c0 = *(const f32x4*)(a0 + cb), c1 = *(const f32x4*)(a0 + cb + 4); const f32x4 x0 = acc[ai][0][m][0], x1 = acc[ai][0][m][1];
; #pragma unroll
;                   for (int j = 0; j < 4; ++j) { av[j] = sigmoidf_(c0[j] + x0[j]); av[4 + j] = sigmoidf_(c1[j] + x1[j]); } }
;                 { const f32x4 c0 = *(const f32x4*)(k_a + cb), c1 = *(const f32x4*)(k_a + cb + 4);
; #pragma unroll
;                   for (int j = 0; j < 4; ++j) { t[j] = ks[j] * (1.0f + (av[j] - 1.0f) * c0[j]); t[4 + j] = ks[4 + j] * (1.0f + (av[4 + j] - 1.0f) * c1[j]); } }
;                 *(u32x4*)kp = pack8(t);
;                 { const f32x4 c0 = *(const f32x4*)(k_k + cb), c1 = *(const f32x4*)(k_k + cb + 4); const float ri = rinv[row * 8 + (cb >> 6)];
; #pragma unroll
;                   for (int j = 0; j < 4; ++j) { t[j] = ks[j] * c0[j] * ri; t[4 + j] = ks[4 + j] * c1[j] * ri; } }
;                 *(u32x4*)(KK + off) = pack8(t);
; #pragma unroll
;                 for (int e = 0; e < 8; ++e) t[e] = -t[e] * av[e];
;                 *(u32x4*)(NB + off) = pack8(t);
;                 asm volatile("" ::: "memory"); }
	v_and_b32_e32 v115, 0xffff0000, v49
	v_lshlrev_b32_e32 v118, 16, v51
	v_and_b32_e32 v119, 0xffff0000, v51
	v_fma_f32 v45, v110, v45, 1.0
	v_fma_f32 v46, v101, v46, 1.0
	v_fma_f32 v47, v111, v47, 1.0
	v_mul_f32_e32 v40, v40, v112
	v_mul_f32_e32 v43, v44, v114
	v_cvt_pk_bf16_f32 v42, v48, v42
	v_lshl_add_u32 v48, v96, 3, s24
	v_mul_f32_e32 v44, v45, v118
	v_mul_f32_e32 v45, v46, v115
	v_mul_f32_e32 v46, v47, v119
	v_cvt_pk_bf16_f32 v40, v40, v41
	v_cvt_pk_bf16_f32 v41, v43, v45
	v_cvt_pk_bf16_f32 v43, v44, v46
	global_store_dwordx4 v[62:63], v[40:43], off offset:1024
	v_ashrrev_i32_e32 v49, 31, v48
	s_nop 1
	v_mov_b32_e32 v40, v184
	v_mov_b32_e32 v41, v185
	v_mov_b32_e32 v42, v186
	v_mov_b32_e32 v43, v187
	s_nop 1
	v_mov_b32_e32 v44, v188
	v_mov_b32_e32 v45, v189
	v_mov_b32_e32 v46, v190
	v_mov_b32_e32 v47, v191
	v_lshl_add_u64 v[48:49], v[48:49], 2, s[4:5]
	s_nop 1
	v_mov_b32_e32 v98, v230
	v_lshlrev_b64 v[50:51], 9, v[96:97]
	v_lshl_add_u64 v[50:51], v[50:51], 0, v[78:79]
	v_mad_i64_i32 v[48:49], s[26:27], v94, s68, v[76:77]
	v_lshlrev_b64 v[50:51], 1, v[50:51]
	v_lshl_add_u64 v[62:63], v[48:49], 0, v[82:83]
	v_lshl_add_u64 v[48:49], s[50:51], 0, v[50:51]
	v_lshl_add_u64 v[50:51], s[62:63], 0, v[50:51]
	v_mul_f32_e32 v40, v40, v112
	v_mul_f32_e32 v44, v44, v116
	v_mul_f32_e32 v41, v41, v113
	v_mul_f32_e32 v45, v45, v117
	v_mul_f32_e32 v42, v42, v114
	v_mul_f32_e32 v46, v46, v118
	v_mul_f32_e32 v43, v43, v115
	v_mul_f32_e32 v47, v47, v119
	v_mul_f32_e32 v96, v40, v98
	v_mul_f32_e32 v44, v98, v44
	v_mul_f32_e32 v97, v41, v98
	v_mul_f32_e32 v45, v98, v45
	v_mul_f32_e32 v99, v42, v98
	v_mul_f32_e32 v46, v98, v46
	v_mul_f32_e32 v100, v43, v98
	v_mul_f32_e32 v47, v98, v47
	v_cvt_pk_bf16_f32 v40, v96, v97
	v_cvt_pk_bf16_f32 v41, v99, v100
	v_cvt_pk_bf16_f32 v42, v44, v45
	v_cvt_pk_bf16_f32 v43, v46, v47
	v_mul_f32_e64 v52, v52, -v96
	v_mul_f32_e64 v54, v54, -v97
	v_mul_f32_e64 v58, v58, -v99
	v_mul_f32_e64 v60, v60, -v100
	v_mul_f32_e64 v44, v53, -v44
	v_mul_f32_e64 v45, v55, -v45
	v_mul_f32_e64 v46, v59, -v46
	v_mul_f32_e64 v47, v61, -v47
	global_store_dwordx4 v[48:49], v[40:43], off
	s_nop 1
	v_cvt_pk_bf16_f32 v40, v52, v54
	v_cvt_pk_bf16_f32 v41, v58, v60
	v_cvt_pk_bf16_f32 v42, v44, v45
	v_cvt_pk_bf16_f32 v43, v46, v47
	global_store_dwordx4 v[50:51], v[40:43], off
	s_nop 1
	v_mov_b32_e32 v40, v208
	v_mov_b32_e32 v41, v209
	v_mov_b32_e32 v42, v210
	v_mov_b32_e32 v43, v211
	s_nop 1
	v_mov_b32_e32 v44, v156
	v_mov_b32_e32 v45, v157
	v_mov_b32_e32 v46, v158
	v_mov_b32_e32 v47, v159
	s_nop 1
	v_mov_b32_e32 v48, v160
	v_mov_b32_e32 v49, v161
	v_mov_b32_e32 v50, v162
	v_mov_b32_e32 v51, v163
	s_nop 1
	v_mov_b32_e32 v52, v164
	v_mov_b32_e32 v53, v165
	v_mov_b32_e32 v54, v166
	v_mov_b32_e32 v55, v167
	s_nop 1
	v_mov_b32_e32 v58, v168
	v_mov_b32_e32 v59, v169
	v_mov_b32_e32 v60, v170
	v_mov_b32_e32 v61, v171
	v_and_b32_e32 v97, 0xffff0000, v40
	v_add_f32_e32 v33, v33, v45
	v_add_f32_e32 v36, v36, v48
	v_add_f32_e32 v37, v37, v49
	v_add_f32_e32 v32, v32, v44
	v_add_f32_e32 v34, v34, v46
	v_mul_f32_e32 v36, 0xbfb8aa3b, v36
	v_mul_f32_e32 v33, 0xbfb8aa3b, v33
	v_mul_f32_e32 v37, 0xbfb8aa3b, v37
	v_add_f32_e32 v38, v38, v50
	v_add_f32_e32 v35, v35, v47
	v_add_f32_e32 v39, v39, v51
	v_mul_f32_e32 v32, 0xbfb8aa3b, v32
	v_mul_f32_e32 v34, 0xbfb8aa3b, v34
	v_exp_f32_e32 v36, v36
	v_exp_f32_e32 v33, v33
	v_exp_f32_e32 v37, v37
	v_mul_f32_e32 v38, 0xbfb8aa3b, v38
	v_mul_f32_e32 v35, 0xbfb8aa3b, v35
	v_mul_f32_e32 v39, 0xbfb8aa3b, v39
	v_exp_f32_e32 v32, v32
	v_exp_f32_e32 v34, v34
	v_exp_f32_e32 v38, v38
	v_exp_f32_e32 v35, v35
	v_exp_f32_e32 v39, v39
	v_add_f32_e32 v36, 1.0, v36
	v_add_f32_e32 v33, 1.0, v33
	v_add_f32_e32 v37, 1.0, v37
	v_add_f32_e32 v32, 1.0, v32
	v_add_f32_e32 v34, 1.0, v34
	v_rcp_f32_e32 v45, v36
	v_rcp_f32_e32 v46, v33
	v_rcp_f32_e32 v47, v37
	v_add_f32_e32 v38, 1.0, v38
	v_add_f32_e32 v35, 1.0, v35
	v_add_f32_e32 v39, 1.0, v39
	v_rcp_f32_e32 v44, v32
	v_rcp_f32_e32 v48, v34
	v_rcp_f32_e32 v49, v38
	v_rcp_f32_e32 v50, v35
	v_rcp_f32_e32 v51, v39
	v_add_f32_e32 v33, -1.0, v45
	v_add_f32_e32 v34, -1.0, v46
	v_add_f32_e32 v35, -1.0, v47
	v_lshlrev_b32_e32 v100, 16, v42
	v_and_b32_e32 v101, 0xffff0000, v42
	v_add_f32_e32 v32, -1.0, v44
	v_add_f32_e32 v36, -1.0, v48
	v_fma_f32 v33, v58, v33, 1.0
	v_fma_f32 v34, v53, v34, 1.0
	v_fma_f32 v35, v59, v35, 1.0
	v_lshlrev_b32_e32 v96, 16, v40
	v_lshlrev_b32_e32 v98, 16, v41
	v_add_f32_e32 v37, -1.0, v49
	v_add_f32_e32 v38, -1.0, v50
	v_add_f32_e32 v39, -1.0, v51
	v_fma_f32 v32, v52, v32, 1.0
	v_fma_f32 v36, v54, v36, 1.0
	v_mul_f32_e32 v40, v33, v100
	v_mul_f32_e32 v33, v34, v97
	v_mul_f32_e32 v34, v35, v101
	v_and_b32_e32 v99, 0xffff0000, v41
	v_lshlrev_b32_e32 v108, 16, v43
	v_and_b32_e32 v109, 0xffff0000, v43
	v_fma_f32 v37, v60, v37, 1.0
	v_fma_f32 v38, v55, v38, 1.0
	v_fma_f32 v39, v61, v39, 1.0
	v_mul_f32_e32 v32, v32, v96
	v_mul_f32_e32 v35, v36, v98
	v_cvt_pk_bf16_f32 v34, v40, v34
	v_lshl_add_u32 v40, v94, 3, s24
	v_mul_f32_e32 v36, v37, v108
	v_mul_f32_e32 v37, v38, v99
	v_mul_f32_e32 v38, v39, v109
	v_cvt_pk_bf16_f32 v32, v32, v33
	v_cvt_pk_bf16_f32 v33, v35, v37
	v_cvt_pk_bf16_f32 v35, v36, v38
	global_store_dwordx4 v[62:63], v[32:35], off offset:1024
	v_ashrrev_i32_e32 v41, 31, v40
	s_nop 1
	v_mov_b32_e32 v32, v184
	v_mov_b32_e32 v33, v185
	v_mov_b32_e32 v34, v186
	v_mov_b32_e32 v35, v187
	s_nop 1
	v_mov_b32_e32 v36, v188
	v_mov_b32_e32 v37, v189
	v_mov_b32_e32 v38, v190
	v_mov_b32_e32 v39, v191
	v_lshl_add_u64 v[40:41], v[40:41], 2, s[4:5]
	s_nop 1
	v_mov_b32_e32 v54, v231
	v_lshlrev_b64 v[42:43], 9, v[94:95]
	v_lshl_add_u64 v[42:43], v[42:43], 0, v[78:79]
; __device__ __forceinline__ void unpack8(const u32x4 w, float (&f)[8]) { f[0] = bflo(w.x); f[1] = bfhi(w.x); f[2] = bflo(w.y); f[3] = bfhi(w.y); f[4] = bflo(w.z); f[5] = bfhi(w.z); f[6] = bflo(w.w); f[7] = bfhi(w.w); }
; __device__ __forceinline__ u32x4 pack8(const float (&f)[8]) { u32x4 o; o.x = pk2(f[0], f[1]); o.y = pk2(f[2], f[3]); o.z = pk2(f[4], f[5]); o.w = pk2(f[6], f[7]); return o; }
; __device__ __forceinline__ float sigmoidf_(float x) { return __builtin_amdgcn_rcpf(1.0f + __expf(-x)); }
;     __device__ __forceinline__ void operator()(const f32x4 (&acc)[2][2][4][2], const Unit& u, int wr, int wc, int fr, int fq) const {
;     ...
;             for (int m = 0; m < 4; ++m) { const int row = row0 + ai * HALF + m * 16; const size_t off = (size_t)row * 512 + cb; bf16_t* kp = RKV + (size_t)row * 1536 + 512 + cb;
;                 float ks[8], av[8], t[8]; unpack8(*(const u32x4*)kp, ks);
;                 { const f32x4 c0 = *(const f32x4*)(a0 + cb), c1 = *(const f32x4*)(a0 + cb + 4); const f32x4 x0 = acc[ai][0][m][0], x1 = acc[ai][0][m][1];
; #pragma unroll
;                   for (int j = 0; j < 4; ++j) { av[j] = sigmoidf_(c0[j] + x0[j]); av[4 + j] = sigmoidf_(c1[j] + x1[j]); } }
;                 { const f32x4 c0 = *(const f32x4*)(k_a + cb), c1 = *(const f32x4*)(k_a + cb + 4);
; #pragma unroll
;                   for (int j = 0; j < 4; ++j) { t[j] = ks[j] * (1.0f + (av[j] - 1.0f) * c0[j]); t[4 + j] = ks[4 + j] * (1.0f + (av[4 + j] - 1.0f) * c1[j]); } }
;                 *(u32x4*)kp = pack8(t);
;                 { const f32x4 c0 = *(const f32x4*)(k_k + cb), c1 = *(const f32x4*)(k_k + cb + 4); const float ri = rinv[row * 8 + (cb >> 6)];
; #pragma unroll
;                   for (int j = 0; j < 4; ++j) { t[j] = ks[j] * c0[j] * ri; t[4 + j] = ks[4 + j] * c1[j] * ri; } }
;                 *(u32x4*)(KK + off) = pack8(t);
; #pragma unroll
;                 for (int e = 0; e < 8; ++e) t[e] = -t[e] * av[e];
;                 *(u32x4*)(NB + off) = pack8(t);
;                 asm volatile("" ::: "memory"); }
	v_mad_i64_i32 v[40:41], s[26:27], v92, s68, v[76:77]
	v_lshlrev_b64 v[42:43], 1, v[42:43]
	v_lshl_add_u64 v[52:53], v[40:41], 0, v[82:83]
	v_lshl_add_u64 v[40:41], s[50:51], 0, v[42:43]
	v_lshl_add_u64 v[42:43], s[62:63], 0, v[42:43]
	v_mul_f32_e32 v32, v32, v96
	v_mul_f32_e32 v36, v36, v100
	v_mul_f32_e32 v33, v33, v97
	v_mul_f32_e32 v37, v37, v101
	v_mul_f32_e32 v34, v34, v98
	v_mul_f32_e32 v38, v38, v108
	v_mul_f32_e32 v35, v35, v99
	v_mul_f32_e32 v39, v39, v109
	v_mul_f32_e32 v55, v32, v54
	v_mul_f32_e32 v36, v54, v36
	v_mul_f32_e32 v58, v33, v54
	v_mul_f32_e32 v37, v54, v37
	v_mul_f32_e32 v59, v34, v54
	v_mul_f32_e32 v38, v54, v38
	v_mul_f32_e32 v60, v35, v54
	v_mul_f32_e32 v39, v54, v39
	v_cvt_pk_bf16_f32 v32, v55, v58
	v_cvt_pk_bf16_f32 v33, v59, v60
	v_cvt_pk_bf16_f32 v34, v36, v37
	v_cvt_pk_bf16_f32 v35, v38, v39
	v_mul_f32_e64 v44, v44, -v55
	v_mul_f32_e64 v46, v46, -v58
	v_mul_f32_e64 v48, v48, -v59
	v_mul_f32_e64 v50, v50, -v60
	v_mul_f32_e64 v36, v45, -v36
	v_mul_f32_e64 v37, v47, -v37
	v_mul_f32_e64 v38, v49, -v38
	v_mul_f32_e64 v39, v51, -v39
	global_store_dwordx4 v[40:41], v[32:35], off
	s_nop 1
	v_cvt_pk_bf16_f32 v32, v44, v46
	v_cvt_pk_bf16_f32 v33, v48, v50
	v_cvt_pk_bf16_f32 v34, v36, v37
	v_cvt_pk_bf16_f32 v35, v38, v39
	global_store_dwordx4 v[42:43], v[32:35], off
	s_nop 1
	v_mov_b32_e32 v32, v212
	v_mov_b32_e32 v33, v213
	v_mov_b32_e32 v34, v214
	v_mov_b32_e32 v35, v215
	s_nop 1
	v_mov_b32_e32 v36, v156
	v_mov_b32_e32 v37, v157
	v_mov_b32_e32 v38, v158
	v_mov_b32_e32 v39, v159
	s_nop 1
	v_mov_b32_e32 v40, v160
	v_mov_b32_e32 v41, v161
	v_mov_b32_e32 v42, v162
	v_mov_b32_e32 v43, v163
	s_nop 1
	v_mov_b32_e32 v44, v164
	v_mov_b32_e32 v45, v165
	v_mov_b32_e32 v46, v166
	v_mov_b32_e32 v47, v167
	s_nop 1
	v_mov_b32_e32 v48, v168
	v_mov_b32_e32 v49, v169
	v_mov_b32_e32 v50, v170
	v_mov_b32_e32 v51, v171
	v_and_b32_e32 v55, 0xffff0000, v32
	v_add_f32_e32 v25, v25, v37
	v_add_f32_e32 v28, v28, v40
	v_add_f32_e32 v29, v29, v41
	v_add_f32_e32 v24, v24, v36
	v_add_f32_e32 v26, v26, v38
	v_mul_f32_e32 v28, 0xbfb8aa3b, v28
	v_mul_f32_e32 v25, 0xbfb8aa3b, v25
	v_mul_f32_e32 v29, 0xbfb8aa3b, v29
	v_add_f32_e32 v30, v30, v42
	v_add_f32_e32 v27, v27, v39
	v_add_f32_e32 v31, v31, v43
	v_mul_f32_e32 v24, 0xbfb8aa3b, v24
	v_mul_f32_e32 v26, 0xbfb8aa3b, v26
	v_exp_f32_e32 v28, v28
	v_exp_f32_e32 v25, v25
	v_exp_f32_e32 v29, v29
	v_mul_f32_e32 v30, 0xbfb8aa3b, v30
	v_mul_f32_e32 v27, 0xbfb8aa3b, v27
	v_mul_f32_e32 v31, 0xbfb8aa3b, v31
	v_exp_f32_e32 v24, v24
	v_exp_f32_e32 v26, v26
	v_exp_f32_e32 v30, v30
	v_exp_f32_e32 v27, v27
	v_exp_f32_e32 v31, v31
	v_add_f32_e32 v28, 1.0, v28
	v_add_f32_e32 v25, 1.0, v25
	v_add_f32_e32 v29, 1.0, v29
	v_add_f32_e32 v24, 1.0, v24
	v_add_f32_e32 v26, 1.0, v26
	v_rcp_f32_e32 v37, v28
	v_rcp_f32_e32 v38, v25
	v_rcp_f32_e32 v39, v29
	v_add_f32_e32 v30, 1.0, v30
	v_add_f32_e32 v27, 1.0, v27
	v_add_f32_e32 v31, 1.0, v31
	v_rcp_f32_e32 v36, v24
	v_rcp_f32_e32 v40, v26
	v_rcp_f32_e32 v41, v30
	v_rcp_f32_e32 v42, v27
	v_rcp_f32_e32 v43, v31
	v_add_f32_e32 v25, -1.0, v37
	v_add_f32_e32 v26, -1.0, v38
	v_add_f32_e32 v27, -1.0, v39
	v_lshlrev_b32_e32 v60, 16, v34
	v_and_b32_e32 v61, 0xffff0000, v34
	v_add_f32_e32 v24, -1.0, v36
	v_add_f32_e32 v28, -1.0, v40
	v_fma_f32 v25, v48, v25, 1.0
	v_fma_f32 v26, v45, v26, 1.0
	v_fma_f32 v27, v49, v27, 1.0
	v_lshlrev_b32_e32 v54, 16, v32
	v_lshlrev_b32_e32 v58, 16, v33
	v_add_f32_e32 v29, -1.0, v41
	v_add_f32_e32 v30, -1.0, v42
	v_add_f32_e32 v31, -1.0, v43
	v_fma_f32 v24, v44, v24, 1.0
	v_fma_f32 v28, v46, v28, 1.0
	v_mul_f32_e32 v32, v25, v60
	v_mul_f32_e32 v25, v26, v55
	v_mul_f32_e32 v26, v27, v61
	v_and_b32_e32 v59, 0xffff0000, v33
	v_lshlrev_b32_e32 v62, 16, v35
	v_and_b32_e32 v63, 0xffff0000, v35
	v_fma_f32 v29, v50, v29, 1.0
	v_fma_f32 v30, v47, v30, 1.0
	v_fma_f32 v31, v51, v31, 1.0
	v_mul_f32_e32 v24, v24, v54
	v_mul_f32_e32 v27, v28, v58
	v_cvt_pk_bf16_f32 v26, v32, v26
	v_lshl_add_u32 v32, v92, 3, s24
	v_mul_f32_e32 v28, v29, v62
	v_mul_f32_e32 v29, v30, v59
	v_mul_f32_e32 v30, v31, v63
	v_cvt_pk_bf16_f32 v24, v24, v25
	v_cvt_pk_bf16_f32 v25, v27, v29
	v_cvt_pk_bf16_f32 v27, v28, v30
	global_store_dwordx4 v[52:53], v[24:27], off offset:1024
	v_ashrrev_i32_e32 v33, 31, v32
	s_nop 1
	v_mov_b32_e32 v24, v184
	v_mov_b32_e32 v25, v185
	v_mov_b32_e32 v26, v186
	v_mov_b32_e32 v27, v187
	s_nop 1
	v_mov_b32_e32 v28, v188
	v_mov_b32_e32 v29, v189
	v_mov_b32_e32 v30, v190
	v_mov_b32_e32 v31, v191
	v_lshl_add_u64 v[32:33], v[32:33], 2, s[4:5]
	s_nop 1
	v_mov_b32_e32 v46, v232
	v_lshlrev_b64 v[34:35], 9, v[92:93]
	v_lshl_add_u64 v[34:35], v[34:35], 0, v[78:79]
	v_mad_i64_i32 v[32:33], s[26:27], v90, s68, v[76:77]
	v_lshlrev_b64 v[34:35], 1, v[34:35]
	v_lshl_add_u64 v[44:45], v[32:33], 0, v[82:83]
	v_lshl_add_u64 v[32:33], s[50:51], 0, v[34:35]
	v_lshl_add_u64 v[34:35], s[62:63], 0, v[34:35]
	v_mul_f32_e32 v24, v24, v54
	v_mul_f32_e32 v28, v28, v60
	v_mul_f32_e32 v25, v25, v55
	v_mul_f32_e32 v29, v29, v61
	v_mul_f32_e32 v26, v26, v58
	v_mul_f32_e32 v30, v30, v62
	v_mul_f32_e32 v27, v27, v59
	v_mul_f32_e32 v31, v31, v63
	v_mul_f32_e32 v47, v24, v46
	v_mul_f32_e32 v28, v46, v28
	v_mul_f32_e32 v48, v25, v46
	v_mul_f32_e32 v29, v46, v29
	v_mul_f32_e32 v49, v26, v46
	v_mul_f32_e32 v30, v46, v30
	v_mul_f32_e32 v50, v27, v46
	v_mul_f32_e32 v31, v46, v31
	v_cvt_pk_bf16_f32 v24, v47, v48
	v_cvt_pk_bf16_f32 v25, v49, v50
	v_cvt_pk_bf16_f32 v26, v28, v29
	v_cvt_pk_bf16_f32 v27, v30, v31
	v_mul_f32_e64 v36, v36, -v47
	v_mul_f32_e64 v38, v38, -v48
	v_mul_f32_e64 v40, v40, -v49
	v_mul_f32_e64 v42, v42, -v50
	v_mul_f32_e64 v28, v37, -v28
	v_mul_f32_e64 v29, v39, -v29
	v_mul_f32_e64 v30, v41, -v30
; __device__ __forceinline__ void unpack8(const u32x4 w, float (&f)[8]) { f[0] = bflo(w.x); f[1] = bfhi(w.x); f[2] = bflo(w.y); f[3] = bfhi(w.y); f[4] = bflo(w.z); f[5] = bfhi(w.z); f[6] = bflo(w.w); f[7] = bfhi(w.w); }
; __device__ __forceinline__ u32x4 pack8(const float (&f)[8]) { u32x4 o; o.x = pk2(f[0], f[1]); o.y = pk2(f[2], f[3]); o.z = pk2(f[4], f[5]); o.w = pk2(f[6], f[7]); return o; }
; __device__ __forceinline__ float sigmoidf_(float x) { return __builtin_amdgcn_rcpf(1.0f + __expf(-x)); }
;     __device__ __forceinline__ void operator()(const f32x4 (&acc)[2][2][4][2], const Unit& u, int wr, int wc, int fr, int fq) const {
;     ...
;             for (int m = 0; m < 4; ++m) { const int row = row0 + ai * HALF + m * 16; const size_t off = (size_t)row * 512 + cb; bf16_t* kp = RKV + (size_t)row * 1536 + 512 + cb;
;                 float ks[8], av[8], t[8]; unpack8(*(const u32x4*)kp, ks);
;                 { const f32x4 c0 = *(const f32x4*)(a0 + cb), c1 = *(const f32x4*)(a0 + cb + 4); const f32x4 x0 = acc[ai][0][m][0], x1 = acc[ai][0][m][1];
; #pragma unroll
;                   for (int j = 0; j < 4; ++j) { av[j] = sigmoidf_(c0[j] + x0[j]); av[4 + j] = sigmoidf_(c1[j] + x1[j]); } }
;                 { const f32x4 c0 = *(const f32x4*)(k_a + cb), c1 = *(const f32x4*)(k_a + cb + 4);
; #pragma unroll
;                   for (int j = 0; j < 4; ++j) { t[j] = ks[j] * (1.0f + (av[j] - 1.0f) * c0[j]); t[4 + j] = ks[4 + j] * (1.0f + (av[4 + j] - 1.0f) * c1[j]); } }
;                 *(u32x4*)kp = pack8(t);
;                 { const f32x4 c0 = *(const f32x4*)(k_k + cb), c1 = *(const f32x4*)(k_k + cb + 4); const float ri = rinv[row * 8 + (cb >> 6)];
; #pragma unroll
;                   for (int j = 0; j < 4; ++j) { t[j] = ks[j] * c0[j] * ri; t[4 + j] = ks[4 + j] * c1[j] * ri; } }
;                 *(u32x4*)(KK + off) = pack8(t);
; #pragma unroll
;                 for (int e = 0; e < 8; ++e) t[e] = -t[e] * av[e];
;                 *(u32x4*)(NB + off) = pack8(t);
;                 asm volatile("" ::: "memory"); }
	v_mul_f32_e64 v31, v43, -v31
	global_store_dwordx4 v[32:33], v[24:27], off
	s_nop 1
	v_cvt_pk_bf16_f32 v24, v36, v38
	v_cvt_pk_bf16_f32 v25, v40, v42
	v_cvt_pk_bf16_f32 v26, v28, v29
	v_cvt_pk_bf16_f32 v27, v30, v31
	global_store_dwordx4 v[34:35], v[24:27], off
	s_nop 1
	v_mov_b32_e32 v24, v216
	v_mov_b32_e32 v25, v217
	v_mov_b32_e32 v26, v218
	v_mov_b32_e32 v27, v219
	s_nop 1
	v_mov_b32_e32 v28, v156
	v_mov_b32_e32 v29, v157
	v_mov_b32_e32 v30, v158
	v_mov_b32_e32 v31, v159
	s_nop 1
	v_mov_b32_e32 v32, v160
	v_mov_b32_e32 v33, v161
	v_mov_b32_e32 v34, v162
	v_mov_b32_e32 v35, v163
	s_nop 1
	v_mov_b32_e32 v36, v164
	v_mov_b32_e32 v37, v165
	v_mov_b32_e32 v38, v166
	v_mov_b32_e32 v39, v167
	s_nop 1
	v_mov_b32_e32 v40, v168
	v_mov_b32_e32 v41, v169
	v_mov_b32_e32 v42, v170
	v_mov_b32_e32 v43, v171
	v_and_b32_e32 v47, 0xffff0000, v24
	v_add_f32_e32 v17, v17, v29
	v_add_f32_e32 v20, v20, v32
	v_add_f32_e32 v21, v21, v33
	v_add_f32_e32 v16, v16, v28
	v_add_f32_e32 v18, v18, v30
	v_mul_f32_e32 v20, 0xbfb8aa3b, v20
	v_mul_f32_e32 v17, 0xbfb8aa3b, v17
	v_mul_f32_e32 v21, 0xbfb8aa3b, v21
	v_add_f32_e32 v22, v22, v34
	v_add_f32_e32 v19, v19, v31
	v_add_f32_e32 v23, v23, v35
	v_mul_f32_e32 v16, 0xbfb8aa3b, v16
	v_mul_f32_e32 v18, 0xbfb8aa3b, v18
	v_exp_f32_e32 v20, v20
	v_exp_f32_e32 v17, v17
	v_exp_f32_e32 v21, v21
	v_mul_f32_e32 v22, 0xbfb8aa3b, v22
	v_mul_f32_e32 v19, 0xbfb8aa3b, v19
	v_mul_f32_e32 v23, 0xbfb8aa3b, v23
	v_exp_f32_e32 v16, v16
	v_exp_f32_e32 v18, v18
	v_exp_f32_e32 v22, v22
	v_exp_f32_e32 v19, v19
	v_exp_f32_e32 v23, v23
	v_add_f32_e32 v20, 1.0, v20
	v_add_f32_e32 v17, 1.0, v17
	v_add_f32_e32 v21, 1.0, v21
	v_add_f32_e32 v16, 1.0, v16
	v_add_f32_e32 v18, 1.0, v18
	v_rcp_f32_e32 v29, v20
	v_rcp_f32_e32 v30, v17
	v_rcp_f32_e32 v31, v21
	v_add_f32_e32 v22, 1.0, v22
	v_add_f32_e32 v19, 1.0, v19
	v_add_f32_e32 v23, 1.0, v23
	v_rcp_f32_e32 v28, v16
	v_rcp_f32_e32 v32, v18
	v_rcp_f32_e32 v33, v22
	v_rcp_f32_e32 v34, v19
	v_rcp_f32_e32 v35, v23
	v_add_f32_e32 v17, -1.0, v29
	v_add_f32_e32 v18, -1.0, v30
	v_add_f32_e32 v19, -1.0, v31
	v_lshlrev_b32_e32 v50, 16, v26
	v_and_b32_e32 v51, 0xffff0000, v26
	v_add_f32_e32 v16, -1.0, v28
	v_add_f32_e32 v20, -1.0, v32
	v_fma_f32 v17, v40, v17, 1.0
	v_fma_f32 v18, v37, v18, 1.0
	v_fma_f32 v19, v41, v19, 1.0
	v_lshlrev_b32_e32 v46, 16, v24
	v_lshlrev_b32_e32 v48, 16, v25
	v_add_f32_e32 v21, -1.0, v33
	v_add_f32_e32 v22, -1.0, v34
	v_add_f32_e32 v23, -1.0, v35
	v_fma_f32 v16, v36, v16, 1.0
	v_fma_f32 v20, v38, v20, 1.0
	v_mul_f32_e32 v24, v17, v50
	v_mul_f32_e32 v17, v18, v47
	v_mul_f32_e32 v18, v19, v51
	v_and_b32_e32 v49, 0xffff0000, v25
	v_lshlrev_b32_e32 v52, 16, v27
	v_and_b32_e32 v53, 0xffff0000, v27
	v_fma_f32 v21, v42, v21, 1.0
	v_fma_f32 v22, v39, v22, 1.0
	v_fma_f32 v23, v43, v23, 1.0
	v_mul_f32_e32 v16, v16, v46
	v_mul_f32_e32 v19, v20, v48
	v_cvt_pk_bf16_f32 v18, v24, v18
	v_lshl_add_u32 v24, v90, 3, s24
	v_mul_f32_e32 v20, v21, v52
	v_mul_f32_e32 v21, v22, v49
	v_mul_f32_e32 v22, v23, v53
	v_cvt_pk_bf16_f32 v16, v16, v17
	v_cvt_pk_bf16_f32 v17, v19, v21
	v_cvt_pk_bf16_f32 v19, v20, v22
	global_store_dwordx4 v[44:45], v[16:19], off offset:1024
	v_ashrrev_i32_e32 v25, 31, v24
	s_nop 1
	v_mov_b32_e32 v16, v184
	v_mov_b32_e32 v17, v185
	v_mov_b32_e32 v18, v186
	v_mov_b32_e32 v19, v187
	s_nop 1
	v_mov_b32_e32 v20, v188
	v_mov_b32_e32 v21, v189
	v_mov_b32_e32 v22, v190
	v_mov_b32_e32 v23, v191
	v_lshl_add_u64 v[24:25], v[24:25], 2, s[4:5]
	s_nop 1
	v_mov_b32_e32 v38, v233
	v_lshlrev_b64 v[26:27], 9, v[90:91]
	v_lshl_add_u64 v[26:27], v[26:27], 0, v[78:79]
	v_mad_i64_i32 v[24:25], s[26:27], v88, s68, v[76:77]
	v_lshlrev_b64 v[26:27], 1, v[26:27]
	v_lshl_add_u64 v[36:37], v[24:25], 0, v[82:83]
	v_lshl_add_u64 v[24:25], s[50:51], 0, v[26:27]
	v_lshl_add_u64 v[26:27], s[62:63], 0, v[26:27]
	v_mul_f32_e32 v16, v16, v46
	v_mul_f32_e32 v20, v20, v50
	v_mul_f32_e32 v17, v17, v47
	v_mul_f32_e32 v21, v21, v51
	v_mul_f32_e32 v18, v18, v48
	v_mul_f32_e32 v22, v22, v52
	v_mul_f32_e32 v19, v19, v49
	v_mul_f32_e32 v23, v23, v53
	v_mul_f32_e32 v39, v16, v38
	v_mul_f32_e32 v20, v38, v20
	v_mul_f32_e32 v40, v17, v38
	v_mul_f32_e32 v21, v38, v21
	v_mul_f32_e32 v41, v18, v38
	v_mul_f32_e32 v22, v38, v22
	v_mul_f32_e32 v42, v19, v38
	v_mul_f32_e32 v23, v38, v23
	v_cvt_pk_bf16_f32 v16, v39, v40
	v_cvt_pk_bf16_f32 v17, v41, v42
	v_cvt_pk_bf16_f32 v18, v20, v21
	v_cvt_pk_bf16_f32 v19, v22, v23
	v_mul_f32_e64 v28, v28, -v39
	v_mul_f32_e64 v30, v30, -v40
	v_mul_f32_e64 v32, v32, -v41
	v_mul_f32_e64 v34, v34, -v42
	v_mul_f32_e64 v20, v29, -v20
	v_mul_f32_e64 v21, v31, -v21
	v_mul_f32_e64 v22, v33, -v22
	v_mul_f32_e64 v23, v35, -v23
	global_store_dwordx4 v[24:25], v[16:19], off
	s_nop 1
	v_cvt_pk_bf16_f32 v16, v28, v30
	v_cvt_pk_bf16_f32 v17, v32, v34
	v_cvt_pk_bf16_f32 v18, v20, v21
	v_cvt_pk_bf16_f32 v19, v22, v23
	global_store_dwordx4 v[26:27], v[16:19], off
	s_nop 1
	v_mov_b32_e32 v16, v220
	v_mov_b32_e32 v17, v221
	v_mov_b32_e32 v18, v222
	v_mov_b32_e32 v19, v223
	s_nop 1
	v_mov_b32_e32 v20, v156
	v_mov_b32_e32 v21, v157
	v_mov_b32_e32 v22, v158
	v_mov_b32_e32 v23, v159
	s_nop 1
	v_mov_b32_e32 v24, v160
	v_mov_b32_e32 v25, v161
	v_mov_b32_e32 v26, v162
	v_mov_b32_e32 v27, v163
	s_nop 1
	v_mov_b32_e32 v28, v164
	v_mov_b32_e32 v29, v165
	v_mov_b32_e32 v30, v166
	v_mov_b32_e32 v31, v167
	s_nop 1
	v_mov_b32_e32 v32, v168
	v_mov_b32_e32 v33, v169
	v_mov_b32_e32 v34, v170
	v_mov_b32_e32 v35, v171
	v_and_b32_e32 v39, 0xffff0000, v16
	v_add_f32_e32 v9, v9, v21
	v_add_f32_e32 v12, v12, v24
	v_add_f32_e32 v13, v13, v25
	v_add_f32_e32 v8, v8, v20
	v_add_f32_e32 v10, v10, v22
	v_mul_f32_e32 v12, 0xbfb8aa3b, v12
; __device__ __forceinline__ void unpack8(const u32x4 w, float (&f)[8]) { f[0] = bflo(w.x); f[1] = bfhi(w.x); f[2] = bflo(w.y); f[3] = bfhi(w.y); f[4] = bflo(w.z); f[5] = bfhi(w.z); f[6] = bflo(w.w); f[7] = bfhi(w.w); }
; __device__ __forceinline__ u32x4 pack8(const float (&f)[8]) { u32x4 o; o.x = pk2(f[0], f[1]); o.y = pk2(f[2], f[3]); o.z = pk2(f[4], f[5]); o.w = pk2(f[6], f[7]); return o; }
; __device__ __forceinline__ float sigmoidf_(float x) { return __builtin_amdgcn_rcpf(1.0f + __expf(-x)); }
;     __device__ __forceinline__ void operator()(const f32x4 (&acc)[2][2][4][2], const Unit& u, int wr, int wc, int fr, int fq) const {
;     ...
;             for (int m = 0; m < 4; ++m) { const int row = row0 + ai * HALF + m * 16; const size_t off = (size_t)row * 512 + cb; bf16_t* kp = RKV + (size_t)row * 1536 + 512 + cb;
;                 float ks[8], av[8], t[8]; unpack8(*(const u32x4*)kp, ks);
;                 { const f32x4 c0 = *(const f32x4*)(a0 + cb), c1 = *(const f32x4*)(a0 + cb + 4); const f32x4 x0 = acc[ai][0][m][0], x1 = acc[ai][0][m][1];
; #pragma unroll
;                   for (int j = 0; j < 4; ++j) { av[j] = sigmoidf_(c0[j] + x0[j]); av[4 + j] = sigmoidf_(c1[j] + x1[j]); } }
;                 { const f32x4 c0 = *(const f32x4*)(k_a + cb), c1 = *(const f32x4*)(k_a + cb + 4);
; #pragma unroll
;                   for (int j = 0; j < 4; ++j) { t[j] = ks[j] * (1.0f + (av[j] - 1.0f) * c0[j]); t[4 + j] = ks[4 + j] * (1.0f + (av[4 + j] - 1.0f) * c1[j]); } }
;                 *(u32x4*)kp = pack8(t);
;                 { const f32x4 c0 = *(const f32x4*)(k_k + cb), c1 = *(const f32x4*)(k_k + cb + 4); const float ri = rinv[row * 8 + (cb >> 6)];
; #pragma unroll
;                   for (int j = 0; j < 4; ++j) { t[j] = ks[j] * c0[j] * ri; t[4 + j] = ks[4 + j] * c1[j] * ri; } }
;                 *(u32x4*)(KK + off) = pack8(t);
; #pragma unroll
;                 for (int e = 0; e < 8; ++e) t[e] = -t[e] * av[e];
;                 *(u32x4*)(NB + off) = pack8(t);
;                 asm volatile("" ::: "memory"); }
	v_mul_f32_e32 v9, 0xbfb8aa3b, v9
	v_mul_f32_e32 v13, 0xbfb8aa3b, v13
	v_add_f32_e32 v14, v14, v26
	v_add_f32_e32 v11, v11, v23
	v_add_f32_e32 v15, v15, v27
	v_mul_f32_e32 v8, 0xbfb8aa3b, v8
	v_mul_f32_e32 v10, 0xbfb8aa3b, v10
	v_exp_f32_e32 v12, v12
	v_exp_f32_e32 v9, v9
	v_exp_f32_e32 v13, v13
	v_mul_f32_e32 v14, 0xbfb8aa3b, v14
	v_mul_f32_e32 v11, 0xbfb8aa3b, v11
	v_mul_f32_e32 v15, 0xbfb8aa3b, v15
	v_exp_f32_e32 v8, v8
	v_exp_f32_e32 v10, v10
	v_exp_f32_e32 v14, v14
	v_exp_f32_e32 v11, v11
	v_exp_f32_e32 v15, v15
	v_add_f32_e32 v12, 1.0, v12
	v_add_f32_e32 v9, 1.0, v9
	v_add_f32_e32 v13, 1.0, v13
	v_add_f32_e32 v8, 1.0, v8
	v_add_f32_e32 v10, 1.0, v10
	v_rcp_f32_e32 v21, v12
	v_rcp_f32_e32 v22, v9
	v_rcp_f32_e32 v23, v13
	v_add_f32_e32 v14, 1.0, v14
	v_add_f32_e32 v11, 1.0, v11
	v_add_f32_e32 v15, 1.0, v15
	v_rcp_f32_e32 v20, v8
	v_rcp_f32_e32 v24, v10
	v_rcp_f32_e32 v25, v14
	v_rcp_f32_e32 v26, v11
	v_rcp_f32_e32 v27, v15
	v_add_f32_e32 v9, -1.0, v21
	v_add_f32_e32 v10, -1.0, v22
	v_add_f32_e32 v11, -1.0, v23
	v_lshlrev_b32_e32 v42, 16, v18
	v_and_b32_e32 v43, 0xffff0000, v18
	v_add_f32_e32 v8, -1.0, v20
	v_add_f32_e32 v12, -1.0, v24
	v_fma_f32 v9, v32, v9, 1.0
	v_fma_f32 v10, v29, v10, 1.0
	v_fma_f32 v11, v33, v11, 1.0
	v_lshlrev_b32_e32 v38, 16, v16
	v_lshlrev_b32_e32 v40, 16, v17
	v_add_f32_e32 v13, -1.0, v25
	v_add_f32_e32 v14, -1.0, v26
	v_add_f32_e32 v15, -1.0, v27
	v_fma_f32 v8, v28, v8, 1.0
	v_fma_f32 v12, v30, v12, 1.0
	v_mul_f32_e32 v16, v9, v42
	v_mul_f32_e32 v9, v10, v39
	v_mul_f32_e32 v10, v11, v43
	v_and_b32_e32 v41, 0xffff0000, v17
	v_lshlrev_b32_e32 v44, 16, v19
	v_and_b32_e32 v45, 0xffff0000, v19
	v_fma_f32 v13, v34, v13, 1.0
	v_fma_f32 v14, v31, v14, 1.0
	v_fma_f32 v15, v35, v15, 1.0
	v_mul_f32_e32 v8, v8, v38
	v_mul_f32_e32 v11, v12, v40
	v_cvt_pk_bf16_f32 v10, v16, v10
	v_lshl_add_u32 v16, v88, 3, s24
	v_mul_f32_e32 v12, v13, v44
	v_mul_f32_e32 v13, v14, v41
	v_mul_f32_e32 v14, v15, v45
	v_cvt_pk_bf16_f32 v8, v8, v9
	v_cvt_pk_bf16_f32 v9, v11, v13
	v_cvt_pk_bf16_f32 v11, v12, v14
	global_store_dwordx4 v[36:37], v[8:11], off offset:1024
	v_ashrrev_i32_e32 v17, 31, v16
	s_nop 1
	v_mov_b32_e32 v8, v184
	v_mov_b32_e32 v9, v185
	v_mov_b32_e32 v10, v186
	v_mov_b32_e32 v11, v187
	s_nop 1
	v_mov_b32_e32 v12, v188
	v_mov_b32_e32 v13, v189
	v_mov_b32_e32 v14, v190
	v_mov_b32_e32 v15, v191
	v_lshl_add_u64 v[16:17], v[16:17], 2, s[4:5]
	s_nop 1
	v_mov_b32_e32 v30, v234
	v_lshlrev_b64 v[18:19], 9, v[88:89]
	v_lshl_add_u64 v[18:19], v[18:19], 0, v[78:79]
	v_mad_i64_i32 v[16:17], s[26:27], v80, s68, v[76:77]
	v_lshlrev_b64 v[18:19], 1, v[18:19]
	v_lshl_add_u64 v[28:29], v[16:17], 0, v[82:83]
	v_lshl_add_u64 v[16:17], s[50:51], 0, v[18:19]
	v_lshl_add_u64 v[18:19], s[62:63], 0, v[18:19]
	s_mov_b64 s[26:27], s[8:9]
	v_mul_f32_e32 v8, v8, v38
	v_mul_f32_e32 v12, v12, v42
	v_mul_f32_e32 v9, v9, v39
	v_mul_f32_e32 v13, v13, v43
	v_mul_f32_e32 v10, v10, v40
	v_mul_f32_e32 v14, v14, v44
	v_mul_f32_e32 v11, v11, v41
	v_mul_f32_e32 v15, v15, v45
	v_mul_f32_e32 v31, v8, v30
	v_mul_f32_e32 v12, v30, v12
	v_mul_f32_e32 v32, v9, v30
	v_mul_f32_e32 v13, v30, v13
	v_mul_f32_e32 v33, v10, v30
	v_mul_f32_e32 v14, v30, v14
	v_mul_f32_e32 v34, v11, v30
	v_mul_f32_e32 v15, v30, v15
	v_cvt_pk_bf16_f32 v8, v31, v32
	v_cvt_pk_bf16_f32 v9, v33, v34
	v_cvt_pk_bf16_f32 v10, v12, v13
	v_cvt_pk_bf16_f32 v11, v14, v15
	v_mul_f32_e64 v20, v20, -v31
	v_mul_f32_e64 v22, v22, -v32
	v_mul_f32_e64 v24, v24, -v33
	v_mul_f32_e64 v26, v26, -v34
	v_mul_f32_e64 v12, v21, -v12
	v_mul_f32_e64 v13, v23, -v13
	v_mul_f32_e64 v14, v25, -v14
	v_mul_f32_e64 v15, v27, -v15
	global_store_dwordx4 v[16:17], v[8:11], off
	s_nop 1
	v_cvt_pk_bf16_f32 v8, v20, v22
	v_cvt_pk_bf16_f32 v9, v24, v26
	v_cvt_pk_bf16_f32 v10, v12, v13
	v_cvt_pk_bf16_f32 v11, v14, v15
	global_store_dwordx4 v[18:19], v[8:11], off
	s_nop 1
	v_mov_b32_e32 v8, v224
	v_mov_b32_e32 v9, v225
	v_mov_b32_e32 v10, v226
	v_mov_b32_e32 v11, v227
	s_nop 1
	v_mov_b32_e32 v12, v156
	v_mov_b32_e32 v13, v157
	v_mov_b32_e32 v14, v158
	v_mov_b32_e32 v15, v159
	s_nop 1
	v_mov_b32_e32 v16, v160
; __device__ __forceinline__ void unpack8(const u32x4 w, float (&f)[8]) { f[0] = bflo(w.x); f[1] = bfhi(w.x); f[2] = bflo(w.y); f[3] = bfhi(w.y); f[4] = bflo(w.z); f[5] = bfhi(w.z); f[6] = bflo(w.w); f[7] = bfhi(w.w); }
; __device__ __forceinline__ u32x4 pack8(const float (&f)[8]) { u32x4 o; o.x = pk2(f[0], f[1]); o.y = pk2(f[2], f[3]); o.z = pk2(f[4], f[5]); o.w = pk2(f[6], f[7]); return o; }
; __device__ __forceinline__ float sigmoidf_(float x) { return __builtin_amdgcn_rcpf(1.0f + __expf(-x)); }
;     __device__ __forceinline__ void operator()(const f32x4 (&acc)[2][2][4][2], const Unit& u, int wr, int wc, int fr, int fq) const {
;     ...
;             for (int m = 0; m < 4; ++m) { const int row = row0 + ai * HALF + m * 16; const size_t off = (size_t)row * 512 + cb; bf16_t* kp = RKV + (size_t)row * 1536 + 512 + cb;
;                 float ks[8], av[8], t[8]; unpack8(*(const u32x4*)kp, ks);
;                 { const f32x4 c0 = *(const f32x4*)(a0 + cb), c1 = *(const f32x4*)(a0 + cb + 4); const f32x4 x0 = acc[ai][0][m][0], x1 = acc[ai][0][m][1];
; #pragma unroll
;                   for (int j = 0; j < 4; ++j) { av[j] = sigmoidf_(c0[j] + x0[j]); av[4 + j] = sigmoidf_(c1[j] + x1[j]); } }
;                 { const f32x4 c0 = *(const f32x4*)(k_a + cb), c1 = *(const f32x4*)(k_a + cb + 4);
; #pragma unroll
;                   for (int j = 0; j < 4; ++j) { t[j] = ks[j] * (1.0f + (av[j] - 1.0f) * c0[j]); t[4 + j] = ks[4 + j] * (1.0f + (av[4 + j] - 1.0f) * c1[j]); } }
;                 *(u32x4*)kp = pack8(t);
;                 { const f32x4 c0 = *(const f32x4*)(k_k + cb), c1 = *(const f32x4*)(k_k + cb + 4); const float ri = rinv[row * 8 + (cb >> 6)];
; #pragma unroll
;                   for (int j = 0; j < 4; ++j) { t[j] = ks[j] * c0[j] * ri; t[4 + j] = ks[4 + j] * c1[j] * ri; } }
;                 *(u32x4*)(KK + off) = pack8(t);
; #pragma unroll
;                 for (int e = 0; e < 8; ++e) t[e] = -t[e] * av[e];
;                 *(u32x4*)(NB + off) = pack8(t);
;                 asm volatile("" ::: "memory"); }
	v_mov_b32_e32 v17, v161
	v_mov_b32_e32 v18, v162
	v_mov_b32_e32 v19, v163
	s_nop 1
	v_mov_b32_e32 v20, v164
	v_mov_b32_e32 v21, v165
	v_mov_b32_e32 v22, v166
	v_mov_b32_e32 v23, v167
	s_nop 1
	v_mov_b32_e32 v24, v168
	v_mov_b32_e32 v25, v169
	v_mov_b32_e32 v26, v170
	v_mov_b32_e32 v27, v171
	v_and_b32_e32 v31, 0xffff0000, v8
	v_add_f32_e32 v1, v1, v13
	v_add_f32_e32 v4, v4, v16
	v_add_f32_e32 v5, v5, v17
	v_add_f32_e32 v0, v0, v12
	v_add_f32_e32 v2, v2, v14
	v_mul_f32_e32 v4, 0xbfb8aa3b, v4
	v_mul_f32_e32 v1, 0xbfb8aa3b, v1
	v_mul_f32_e32 v5, 0xbfb8aa3b, v5
	v_add_f32_e32 v6, v6, v18
	v_add_f32_e32 v3, v3, v15
	v_add_f32_e32 v7, v7, v19
	v_mul_f32_e32 v0, 0xbfb8aa3b, v0
	v_mul_f32_e32 v2, 0xbfb8aa3b, v2
	v_exp_f32_e32 v4, v4
	v_exp_f32_e32 v1, v1
	v_exp_f32_e32 v5, v5
	v_mul_f32_e32 v6, 0xbfb8aa3b, v6
	v_mul_f32_e32 v3, 0xbfb8aa3b, v3
	v_mul_f32_e32 v7, 0xbfb8aa3b, v7
	v_exp_f32_e32 v0, v0
	v_exp_f32_e32 v2, v2
	v_exp_f32_e32 v6, v6
	v_exp_f32_e32 v3, v3
	v_exp_f32_e32 v7, v7
	v_add_f32_e32 v4, 1.0, v4
	v_add_f32_e32 v1, 1.0, v1
	v_add_f32_e32 v5, 1.0, v5
	v_add_f32_e32 v0, 1.0, v0
	v_add_f32_e32 v2, 1.0, v2
	v_rcp_f32_e32 v13, v4
	v_rcp_f32_e32 v14, v1
	v_rcp_f32_e32 v15, v5
	v_add_f32_e32 v6, 1.0, v6
	v_add_f32_e32 v3, 1.0, v3
	v_add_f32_e32 v7, 1.0, v7
	v_rcp_f32_e32 v12, v0
	v_rcp_f32_e32 v16, v2
	v_rcp_f32_e32 v17, v6
	v_rcp_f32_e32 v18, v3
	v_rcp_f32_e32 v19, v7
	v_add_f32_e32 v1, -1.0, v13
	v_add_f32_e32 v2, -1.0, v14
	v_add_f32_e32 v3, -1.0, v15
	v_lshlrev_b32_e32 v34, 16, v10
	v_and_b32_e32 v35, 0xffff0000, v10
	v_add_f32_e32 v0, -1.0, v12
	v_add_f32_e32 v4, -1.0, v16
	v_fma_f32 v1, v24, v1, 1.0
	v_fma_f32 v2, v21, v2, 1.0
	v_fma_f32 v3, v25, v3, 1.0
	v_lshlrev_b32_e32 v30, 16, v8
	v_lshlrev_b32_e32 v32, 16, v9
	v_add_f32_e32 v5, -1.0, v17
	v_add_f32_e32 v6, -1.0, v18
	v_add_f32_e32 v7, -1.0, v19
	v_fma_f32 v0, v20, v0, 1.0
	v_fma_f32 v4, v22, v4, 1.0
	v_mul_f32_e32 v8, v1, v34
	v_mul_f32_e32 v1, v2, v31
	v_mul_f32_e32 v2, v3, v35
	v_and_b32_e32 v33, 0xffff0000, v9
	v_lshlrev_b32_e32 v36, 16, v11
	v_and_b32_e32 v37, 0xffff0000, v11
	v_fma_f32 v5, v26, v5, 1.0
	v_fma_f32 v6, v23, v6, 1.0
	v_fma_f32 v7, v27, v7, 1.0
	v_mul_f32_e32 v0, v0, v30
	v_mul_f32_e32 v3, v4, v32
	v_cvt_pk_bf16_f32 v2, v8, v2
	v_lshl_add_u32 v8, v80, 3, s24
	v_mul_f32_e32 v4, v5, v36
	v_mul_f32_e32 v5, v6, v33
	v_mul_f32_e32 v6, v7, v37
	v_cvt_pk_bf16_f32 v0, v0, v1
	v_cvt_pk_bf16_f32 v1, v3, v5
	v_cvt_pk_bf16_f32 v3, v4, v6
	global_store_dwordx4 v[28:29], v[0:3], off offset:1024
	v_ashrrev_i32_e32 v9, 31, v8
	s_nop 1
	v_mov_b32_e32 v0, v184
	v_mov_b32_e32 v1, v185
	v_mov_b32_e32 v2, v186
	v_mov_b32_e32 v3, v187
	s_nop 1
	v_mov_b32_e32 v4, v188
	v_mov_b32_e32 v5, v189
	v_mov_b32_e32 v6, v190
	v_mov_b32_e32 v7, v191
	v_lshl_add_u64 v[8:9], v[8:9], 2, s[4:5]
	s_nop 1
	v_mov_b32_e32 v20, v235
	v_lshlrev_b64 v[8:9], 9, v[80:81]
	v_lshl_add_u64 v[8:9], v[8:9], 0, v[78:79]
	v_lshlrev_b64 v[8:9], 1, v[8:9]
	v_lshl_add_u64 v[10:11], s[50:51], 0, v[8:9]
	v_lshl_add_u64 v[8:9], s[62:63], 0, v[8:9]
	s_mov_b64 s[24:25], s[0:1]
	v_mul_f32_e32 v0, v0, v30
	v_mul_f32_e32 v4, v4, v34
	v_mul_f32_e32 v1, v1, v31
	v_mul_f32_e32 v5, v5, v35
	v_mul_f32_e32 v2, v2, v32
	v_mul_f32_e32 v6, v6, v36
	v_mul_f32_e32 v3, v3, v33
	v_mul_f32_e32 v7, v7, v37
	v_mul_f32_e32 v21, v0, v20
	v_mul_f32_e32 v4, v20, v4
	v_mul_f32_e32 v22, v1, v20
	v_mul_f32_e32 v5, v20, v5
	v_mul_f32_e32 v23, v2, v20
	v_mul_f32_e32 v6, v20, v6
	v_mul_f32_e32 v24, v3, v20
	v_mul_f32_e32 v7, v20, v7
	v_cvt_pk_bf16_f32 v0, v21, v22
	v_cvt_pk_bf16_f32 v1, v23, v24
	v_cvt_pk_bf16_f32 v2, v4, v5
	v_cvt_pk_bf16_f32 v3, v6, v7
	v_mul_f32_e64 v12, v12, -v21
	v_mul_f32_e64 v14, v14, -v22
	v_mul_f32_e64 v16, v16, -v23
	v_mul_f32_e64 v18, v18, -v24
	v_mul_f32_e64 v4, v13, -v4
	v_mul_f32_e64 v5, v15, -v5
	v_mul_f32_e64 v6, v17, -v6
	v_mul_f32_e64 v7, v19, -v7
	global_store_dwordx4 v[10:11], v[0:3], off
	s_nop 1
	v_cvt_pk_bf16_f32 v0, v12, v14
	v_cvt_pk_bf16_f32 v1, v16, v18
	v_cvt_pk_bf16_f32 v2, v4, v5
	v_cvt_pk_bf16_f32 v3, v6, v7
	global_store_dwordx4 v[8:9], v[0:3], off
	s_cbranch_vccz .LBB0_472
